# PF loop also peeled (zero SrcC, bookkeeping among last MFMAs); PG/PH/PF peeled first iteration drops its two leading vmcnt(8), phase prologue drains its stage loads fully; trampoline for the phase-end
# speedup vs baseline: 1.0014x; 1.0014x over previous
; #define PG8_STAGE(bufoff, gbase, voff) do { _Pragma("unroll") for (int _i = 0; _i < 2; ++_i) \
;         __builtin_amdgcn_global_load_lds((const unsigned*)((const char*)(gbase) + (voff)[_i]), (LAS unsigned*)(lds + (bufoff) + ldsw + _i * 8192), 16, 0, 0); } while (0)
; #define PG8_WAIT_V(n) asm volatile("s_waitcnt vmcnt(" #n ")" ::: "memory")
; #define PG8_BAR __builtin_amdgcn_s_barrier()
; template <class Epi, class Sched, bool ALIGN_EPI>
; __device__ __forceinline__ void gemm_phase(LAS unsigned char* lds, const Gemm g, const Sched& S, const Epi& E) {
;     ...
;     const int wid = __builtin_amdgcn_readfirstlane(tid >> 6), lane = tid & 63, wr = wid >> 2, wc = wid & 3, fr = lane & 15, fq = lane >> 4;
;     const int K = g.K, nt = K / BK;
;     unsigned voffA[2], voffB[2];
; #pragma unroll
;     for (int i = 0; i < 2; ++i) { int R, C; stage_rc(tid * 16 + i * 8192, R, C); const int Rb = Epi::PERM ? ((R & ~31) + perm32(R & 31)) : R;
;         voffA[i] = (unsigned)(R * g.lda + C) * 2u; voffB[i] = (unsigned)(Rb * g.ldb + C) * 2u; }
;     const size_t kstep = (size_t)(BK * 2);
;     const size_t hstepA = (size_t)HALF * g.lda * 2, hstepB = (size_t)HALF * g.ldb * 2;
;     const size_t tstepA = 2 * hstepA, tstepB = 2 * hstepB;
;     const unsigned ldsw = (unsigned)wid * 1024u;
;     const int aoff = lds_byte(wr * 64 + fr, fq * 8), boff = lds_byte(wc * 32 + fr, fq * 8);
;     ...
;     Unit cur, nxt; int ui = 0;
;     if (!S.next(0, cur)) return;
;     f32x4 acc[2][2][4][2];
; #pragma unroll
;     for (int a = 0; a < 2; ++a)
; #pragma unroll
;         for (int b = 0; b < 2; ++b)
; #pragma unroll
;             for (int m = 0; m < 4; ++m)
; #pragma unroll
;                 for (int n = 0; n < 2; ++n) acc[a][b][m][n] = (f32x4){0.f, 0.f, 0.f, 0.f};
;     bf16x8 At[4][2], B0[2][2], B1[2][2];
;     const char* cA = (const char*)g.A + (size_t)cur.pm * tstepA; const char* cB = (const char*)g.Bt + (size_t)cur.pn * tstepB;
;     PG8_STAGE(PG8_SB(0, 0), cB, voffB); PG8_STAGE(PG8_SB(0, 1), cB + hstepB, voffB); PG8_STAGE(PG8_SA(0, 0), cA, voffA); PG8_STAGE(PG8_SA(0, 1), cA + hstepA, voffA);
;     if (wr == 1) PG8_BAR;
;     PG8_WAIT_V(2); PG8_BAR;
;     PG8_STAGE(PG8_SB(1, 0), cB + kstep, voffB); PG8_STAGE(PG8_SA(1, 0), cA + kstep, voffA); PG8_STAGE(PG8_SB(1, 1), cB + hstepB + kstep, voffB);
;     PG8_WAIT_V(6); PG8_BAR;
.LBB0_199:
	s_waitcnt lgkmcnt(0)
	s_add_u32 s16, s38, 0x8100000
	s_addc_u32 s17, s39, 0
	v_bfe_u32 v207, v14, 4, 2
	s_add_u32 s22, s22, 0xe00000
	v_and_b32_e32 v211, 15, v14
	v_lshlrev_b32_e32 v15, 4, v207
	v_lshlrev_b32_e32 v14, 2, v14
	s_addc_u32 s23, s23, 0
	s_and_b32 s6, s8, 3
	s_lshl_b32 s7, s4, 6
	v_lshl_or_b32 v15, v211, 6, v15
	s_lshl_b32 s4, s4, 13
	v_and_b32_e32 v14, 32, v14
	v_bitop3_b32 v16, v15, s4, v14 bitop3:0xde
	s_lshl_b32 s58, s6, 5
	s_lshl_b32 s4, s6, 12
	v_bitop3_b32 v247, v15, s4, v14 bitop3:0xde
	v_writelane_b32 v255, s43, 50
	s_add_u32 s4, s43, 0x5000
	v_writelane_b32 v255, s4, 56
	v_lshl_add_u64 v[4:5], v[4:5], 0, s[12:13]
	v_readlane_b32 s4, v255, 38
	s_addc_u32 s4, s4, 0
	s_add_i32 m0, s49, 0x18000
	v_writelane_b32 v255, s4, 57
	s_waitcnt vmcnt(2)
	s_barrier
	global_load_lds_dwordx4 v[4:5], off
	v_lshl_add_u64 v[2:3], v[2:3], 0, s[12:13]
	s_add_i32 m0, s49, 0x1a000
	s_add_i32 s59, s49, 0x8000
	s_add_i32 s4, s49, 0xa000
	global_load_lds_dwordx4 v[2:3], off
	v_lshl_add_u64 v[0:1], v[0:1], 0, s[12:13]
	s_mov_b32 m0, s59
	s_add_u32 s8, s46, 0x100080
	global_load_lds_dwordx4 v[0:1], off
	v_lshl_add_u64 v[0:1], v[6:7], 0, s[12:13]
	s_mov_b32 m0, s4
	s_addc_u32 s9, s47, 0
	global_load_lds_dwordx4 v[0:1], off
	s_add_i32 m0, s49, 0x1c000
	v_lshl_add_u64 v[0:1], s[8:9], 0, v[216:217]
	global_load_lds_dwordx4 v[0:1], off
	v_lshl_add_u64 v[0:1], s[8:9], 0, v[212:213]
	s_add_i32 m0, s49, 0x1e000
	s_cmpk_lt_u32 s5, 0x100
	global_load_lds_dwordx4 v[0:1], off
	s_cselect_b64 s[38:39], -1, 0
	s_and_b32 s5, s5, 0xffffff00
	s_lshl_b32 s8, s6, 6
	v_lshlrev_b32_e32 v0, 16, v12
	s_or_b32 s5, s8, s5
	v_readlane_b32 s8, v255, 60
	v_and_b32_e32 v0, 0xfffe0000, v0
	v_readlane_b32 s9, v255, 61
	v_lshl_add_u32 v0, v11, 13, v0
	v_and_b32_e32 v1, 1, v12
	s_cmp_eq_u64 s[8:9], 0
	v_lshl_or_b32 v0, v1, 6, v0
	s_cselect_b64 s[42:43], -1, 0
	s_cmp_lg_u64 s[8:9], 0
	v_lshl_add_u32 v220, v13, 1, v0
	v_lshlrev_b32_e32 v0, 16, v8
	s_cselect_b64 s[40:41], -1, 0
	v_and_b32_e32 v0, 0xfffe0000, v0
	s_xor_b64 s[42:43], s[42:43], -1
	s_waitcnt vmcnt(0)
	s_lshl_b32 s8, s6, 7
	v_lshl_add_u32 v0, v9, 13, v0
	v_and_b32_e32 v1, 1, v8
	v_writelane_b32 v255, s42, 58
	s_add_i32 s8, s8, 0
	v_lshl_or_b32 v0, v1, 6, v0
	v_writelane_b32 v255, s43, 59
	v_readlane_b32 s42, v254, 43
	s_add_i32 s87, s8, 0x20400
	s_add_i32 s8, s8, 0x20800
	v_mov_b32_e32 v221, v193
	v_lshl_add_u32 v222, v10, 1, v0
	v_mov_b32_e32 v223, v193
	s_mov_b32 s9, 0
	v_add_u32_e32 v248, 0, v16
	v_readlane_b32 s76, v254, 27
	s_mov_b32 s77, s42
	s_barrier
	v_readlane_b32 s43, v254, 44
	s_branch .LBB0_202

; #define PG8_STAGE(bufoff, gbase, voff) do { _Pragma("unroll") for (int _i = 0; _i < 2; ++_i) \
;         __builtin_amdgcn_global_load_lds((const unsigned*)((const char*)(gbase) + (voff)[_i]), (LAS unsigned*)(lds + (bufoff) + ldsw + _i * 8192), 16, 0, 0); } while (0)
; #define PG8_LDA(dst, b, h) do { _Pragma("unroll") for (int m = 0; m < 4; ++m) _Pragma("unroll") for (int k = 0; k < 2; ++k) dst[m][k] = *(const LAS bf16x8*)(lds + PG8_SA(b, h) + aoff + m * 2048 + k * 1024); } while (0)
; #define PG8_LDB(dst, b, h) do { _Pragma("unroll") for (int n = 0; n < 2; ++n) _Pragma("unroll") for (int k = 0; k < 2; ++k) dst[n][k] = *(const LAS bf16x8*)(lds + PG8_SB(b, h) + boff + n * 2048 + k * 1024); } while (0)
; #define PG8_MMA(ai, bj, At, Bt) do { __builtin_amdgcn_s_setprio(1); _Pragma("unroll") for (int m = 0; m < 4; ++m) _Pragma("unroll") for (int n = 0; n < 2; ++n) _Pragma("unroll") for (int k = 0; k < 2; ++k) \
;         acc[ai][bj][m][n] = __builtin_amdgcn_mfma_f32_16x16x32_bf16(Bt[n][k], At[m][k], acc[ai][bj][m][n], 0, 0, 0); __builtin_amdgcn_s_setprio(0); } while (0)
; #define PG8_WAIT_V(n) asm volatile("s_waitcnt vmcnt(" #n ")" ::: "memory")
; #define PG8_WAIT_L(n) asm volatile("s_waitcnt lgkmcnt(" #n ")" ::: "memory")
; template <class Epi, class Sched, bool ALIGN_EPI>
; __device__ __forceinline__ void gemm_phase(LAS unsigned char* lds, const Gemm g, const Sched& S, const Epi& E) {
;     ...
;         const bool has_next = S.next(ui + 1, nxt);
;         const char* nA = has_next ? (const char*)g.A + (size_t)nxt.pm * tstepA : cA; const char* nB = has_next ? (const char*)g.Bt + (size_t)nxt.pn * tstepB : cB;
;         for (int t = 0; t < nt; t += 2) {
;             const bool last = (t == nt - 2);
;             const char* a1 = cA + (size_t)(t + 1) * kstep;
;             const char* a2 = last ? nA : cA + (size_t)(t + 2) * kstep; const char* b2 = last ? nB : cB + (size_t)(t + 2) * kstep;
;             const char* a3 = a2 + kstep; const char* b3 = b2 + kstep;
;             PG8_LDB(B0, 0, 0); PG8_LDB(B1, 0, 1); PG8_SCHED; PG8_LDA(At, 0, 0); PG8_STAGE(PG8_SA(1, 1), a1 + hstepA, voffA);
;             PG8_WAIT_V(8); PG8_WAIT_L(0); PG8_BAR; PG8_MMA(0, 0, At, B0); PG8_MMA(0, 1, At, B1); PG8_BAR; PG8_SCHED;
;             PG8_LDA(At, 0, 1); PG8_STAGE(PG8_SB(0, 0), b2, voffB); PG8_STAGE(PG8_SB(0, 1), b2 + hstepB, voffB); PG8_STAGE(PG8_SA(0, 0), a2, voffA);
.LBB0_208:
	s_ashr_i32 s81, s80, 31
	s_lshl_b64 s[54:55], s[80:81], 21
	s_add_u32 s84, s33, s54
	s_addc_u32 s85, s51, s55
	s_and_b64 s[54:55], s[42:43], exec
	s_cselect_b32 s56, s85, s45
	s_cselect_b32 s57, s84, s44
	s_ashr_i32 s63, s62, 31
	s_lshl_b64 s[54:55], s[62:63], 21
	v_readlane_b32 s52, v255, 48
	s_add_u32 s90, s52, s54
	s_addc_u32 s91, s48, s55
	s_and_b64 s[54:55], s[42:43], exec
	s_cselect_b32 s63, s91, s47
	s_cselect_b32 s64, s90, s46
	s_add_u32 s44, s44, 0x100080
	s_addc_u32 s45, s45, 0
	s_add_u32 s65, s46, 0x100
	s_addc_u32 s81, s47, 0
	s_mov_b32 s92, -2
	s_add_u32 s46, s44, 0xfff00080
	s_addc_u32 s47, s45, -1
	s_add_i32 s52, 0, 0x10000
	s_cmp_eq_u32 s92, 60
	s_cselect_b32 s55, s56, s47
	s_cselect_b32 s54, s57, s46
	s_cselect_b32 s47, s63, s81
	s_cselect_b32 s46, s64, s65
	s_add_i32 s53, 0, 0x14000
	v_add_u32_e32 v140, s52, v247
	v_add_u32_e32 v156, s53, v247
	ds_read_b128 v[104:107], v140
	ds_read_b128 v[112:115], v140 offset:1024
	ds_read_b128 v[136:139], v140 offset:2048
	ds_read_b128 v[140:143], v140 offset:3072
	ds_read_b128 v[144:147], v156
	ds_read_b128 v[148:151], v156 offset:1024
	ds_read_b128 v[152:155], v156 offset:2048
	ds_read_b128 v[156:159], v156 offset:3072
	v_lshl_add_u64 v[194:195], s[44:45], 0, v[220:221]
	s_add_i32 m0, s49, 0xc000
	ds_read_b128 v[160:163], v248
	ds_read_b128 v[164:167], v248 offset:1024
	ds_read_b128 v[168:171], v248 offset:2048
	ds_read_b128 v[172:175], v248 offset:3072
	ds_read_b128 v[176:179], v248 offset:4096
	ds_read_b128 v[180:183], v248 offset:5120
	ds_read_b128 v[184:187], v248 offset:6144
	ds_read_b128 v[188:191], v248 offset:7168
	global_load_lds_dwordx4 v[194:195], off
	v_lshl_add_u64 v[194:195], s[44:45], 0, v[222:223]
	s_add_i32 m0, s49, 0xe000
	s_nop 0
	global_load_lds_dwordx4 v[194:195], off
	s_waitcnt lgkmcnt(0)
	s_barrier
	s_setprio 1
	s_waitcnt lgkmcnt(0)
	v_mfma_f32_16x16x32_bf16 v[132:135], v[104:107], v[160:163], 0
	v_mfma_f32_16x16x32_bf16 v[128:131], v[136:139], v[160:163], 0
	v_mfma_f32_16x16x32_bf16 v[116:119], v[104:107], v[168:171], 0
	v_mfma_f32_16x16x32_bf16 v[108:111], v[136:139], v[168:171], 0
	v_mfma_f32_16x16x32_bf16 v[96:99], v[104:107], v[176:179], 0
	v_mfma_f32_16x16x32_bf16 v[88:91], v[136:139], v[176:179], 0
	v_mfma_f32_16x16x32_bf16 v[80:83], v[104:107], v[184:187], 0
	v_mfma_f32_16x16x32_bf16 v[72:75], v[136:139], v[184:187], 0
	v_mfma_f32_16x16x32_bf16 v[132:135], v[112:115], v[164:167], v[132:135]
	v_mfma_f32_16x16x32_bf16 v[128:131], v[140:143], v[164:167], v[128:131]
	v_mfma_f32_16x16x32_bf16 v[116:119], v[112:115], v[172:175], v[116:119]
	v_mfma_f32_16x16x32_bf16 v[108:111], v[140:143], v[172:175], v[108:111]
	v_mfma_f32_16x16x32_bf16 v[96:99], v[112:115], v[180:183], v[96:99]
	v_mfma_f32_16x16x32_bf16 v[88:91], v[140:143], v[180:183], v[88:91]
	v_mfma_f32_16x16x32_bf16 v[80:83], v[112:115], v[188:191], v[80:83]
	v_mfma_f32_16x16x32_bf16 v[72:75], v[140:143], v[188:191], v[72:75]
	s_setprio 0
	s_setprio 1
	v_mfma_f32_16x16x32_bf16 v[124:127], v[144:147], v[160:163], 0
	v_mfma_f32_16x16x32_bf16 v[120:123], v[152:155], v[160:163], 0
	v_mfma_f32_16x16x32_bf16 v[100:103], v[144:147], v[168:171], 0
	v_mfma_f32_16x16x32_bf16 v[92:95], v[152:155], v[168:171], 0
	v_mfma_f32_16x16x32_bf16 v[84:87], v[144:147], v[176:179], 0
	v_mfma_f32_16x16x32_bf16 v[76:79], v[152:155], v[176:179], 0
	v_mfma_f32_16x16x32_bf16 v[68:71], v[144:147], v[184:187], 0
	v_mfma_f32_16x16x32_bf16 v[64:67], v[152:155], v[184:187], 0
	v_mfma_f32_16x16x32_bf16 v[124:127], v[148:151], v[164:167], v[124:127]
	v_mfma_f32_16x16x32_bf16 v[120:123], v[156:159], v[164:167], v[120:123]
	v_mfma_f32_16x16x32_bf16 v[100:103], v[148:151], v[172:175], v[100:103]
	v_mfma_f32_16x16x32_bf16 v[92:95], v[156:159], v[172:175], v[92:95]
	v_mfma_f32_16x16x32_bf16 v[84:87], v[148:151], v[180:183], v[84:87]
	v_mfma_f32_16x16x32_bf16 v[76:79], v[156:159], v[180:183], v[76:79]
	v_mfma_f32_16x16x32_bf16 v[68:71], v[148:151], v[188:191], v[68:71]
	v_mfma_f32_16x16x32_bf16 v[64:67], v[156:159], v[188:191], v[64:67]
	s_setprio 0
	s_barrier
	s_add_i32 s52, s52, s50
	v_lshl_add_u64 v[194:195], s[46:47], 0, v[216:217]
	s_mov_b32 m0, s52
	ds_read_b128 v[160:163], v248 offset:16384
	ds_read_b128 v[164:167], v248 offset:17408
	ds_read_b128 v[168:171], v248 offset:18432
	ds_read_b128 v[172:175], v248 offset:19456
	ds_read_b128 v[176:179], v248 offset:20480
	ds_read_b128 v[180:183], v248 offset:21504
	ds_read_b128 v[184:187], v248 offset:22528
	ds_read_b128 v[188:191], v248 offset:23552
	global_load_lds_dwordx4 v[194:195], off
	s_add_i32 m0, s52, 0x2000
	s_add_u32 vcc_lo, s46, 0x100000
	v_lshl_add_u64 v[196:197], s[46:47], 0, v[212:213]
	s_addc_u32 vcc_hi, s47, 0
	s_add_i32 s52, s53, s50
	global_load_lds_dwordx4 v[196:197], off
	v_lshl_add_u64 v[198:199], vcc, 0, v[216:217]
	s_mov_b32 m0, s52
	v_lshl_add_u64 v[200:201], s[54:55], 0, v[214:215]
	global_load_lds_dwordx4 v[198:199], off
	v_lshl_add_u64 v[198:199], vcc, 0, v[212:213]
	s_add_i32 m0, s52, 0x2000
	s_nop 0
	global_load_lds_dwordx4 v[198:199], off
	v_lshl_add_u64 v[198:199], s[54:55], 0, v[218:219]
	s_mov_b32 m0, s49
	s_nop 0
	global_load_lds_dwordx4 v[198:199], off
	s_mov_b32 m0, s67
	s_nop 0
	global_load_lds_dwordx4 v[200:201], off
	s_waitcnt lgkmcnt(0)
	s_barrier
; #define PG8_STAGE(bufoff, gbase, voff) do { _Pragma("unroll") for (int _i = 0; _i < 2; ++_i) \
;         __builtin_amdgcn_global_load_lds((const unsigned*)((const char*)(gbase) + (voff)[_i]), (LAS unsigned*)(lds + (bufoff) + ldsw + _i * 8192), 16, 0, 0); } while (0)
; #define PG8_LDA(dst, b, h) do { _Pragma("unroll") for (int m = 0; m < 4; ++m) _Pragma("unroll") for (int k = 0; k < 2; ++k) dst[m][k] = *(const LAS bf16x8*)(lds + PG8_SA(b, h) + aoff + m * 2048 + k * 1024); } while (0)
; #define PG8_LDB(dst, b, h) do { _Pragma("unroll") for (int n = 0; n < 2; ++n) _Pragma("unroll") for (int k = 0; k < 2; ++k) dst[n][k] = *(const LAS bf16x8*)(lds + PG8_SB(b, h) + boff + n * 2048 + k * 1024); } while (0)
; #define PG8_MMA(ai, bj, At, Bt) do { __builtin_amdgcn_s_setprio(1); _Pragma("unroll") for (int m = 0; m < 4; ++m) _Pragma("unroll") for (int n = 0; n < 2; ++n) _Pragma("unroll") for (int k = 0; k < 2; ++k) \
;         acc[ai][bj][m][n] = __builtin_amdgcn_mfma_f32_16x16x32_bf16(Bt[n][k], At[m][k], acc[ai][bj][m][n], 0, 0, 0); __builtin_amdgcn_s_setprio(0); } while (0)
; #define PG8_WAIT_V(n) asm volatile("s_waitcnt vmcnt(" #n ")" ::: "memory")
; #define PG8_WAIT_L(n) asm volatile("s_waitcnt lgkmcnt(" #n ")" ::: "memory")
; #define PG8_BAR __builtin_amdgcn_s_barrier()
; #define PG8_SCHED __builtin_amdgcn_sched_barrier(0)
; template <class Epi, class Sched, bool ALIGN_EPI>
; __device__ __forceinline__ void gemm_phase(LAS unsigned char* lds, const Gemm g, const Sched& S, const Epi& E) {
;     ...
;             PG8_WAIT_V(8); PG8_WAIT_L(0); PG8_BAR; PG8_MMA(1, 0, At, B0); PG8_MMA(1, 1, At, B1); PG8_BAR; PG8_SCHED;
;             PG8_LDB(B0, 1, 0); PG8_LDB(B1, 1, 1); PG8_SCHED; PG8_LDA(At, 1, 0); PG8_STAGE(PG8_SA(0, 1), a2 + hstepA, voffA);
;             PG8_WAIT_V(8); PG8_WAIT_L(0); PG8_BAR; PG8_MMA(0, 0, At, B0); PG8_MMA(0, 1, At, B1); PG8_BAR; PG8_SCHED;
	s_setprio 1
	s_waitcnt lgkmcnt(0)
	v_mfma_f32_16x16x32_bf16 v[60:63], v[104:107], v[160:163], 0
	v_mfma_f32_16x16x32_bf16 v[56:59], v[136:139], v[160:163], 0
	v_mfma_f32_16x16x32_bf16 v[44:47], v[104:107], v[168:171], 0
	v_mfma_f32_16x16x32_bf16 v[40:43], v[136:139], v[168:171], 0
	v_mfma_f32_16x16x32_bf16 v[32:35], v[104:107], v[176:179], 0
	v_mfma_f32_16x16x32_bf16 v[24:27], v[136:139], v[176:179], 0
	v_mfma_f32_16x16x32_bf16 v[16:19], v[104:107], v[184:187], 0
	v_mfma_f32_16x16x32_bf16 v[8:11], v[136:139], v[184:187], 0
	v_mfma_f32_16x16x32_bf16 v[60:63], v[112:115], v[164:167], v[60:63]
	v_mfma_f32_16x16x32_bf16 v[56:59], v[140:143], v[164:167], v[56:59]
	v_mfma_f32_16x16x32_bf16 v[44:47], v[112:115], v[172:175], v[44:47]
	v_mfma_f32_16x16x32_bf16 v[40:43], v[140:143], v[172:175], v[40:43]
	v_mfma_f32_16x16x32_bf16 v[32:35], v[112:115], v[180:183], v[32:35]
	v_mfma_f32_16x16x32_bf16 v[24:27], v[140:143], v[180:183], v[24:27]
	v_mfma_f32_16x16x32_bf16 v[16:19], v[112:115], v[188:191], v[16:19]
	v_mfma_f32_16x16x32_bf16 v[8:11], v[140:143], v[188:191], v[8:11]
	s_setprio 0
	s_setprio 1
	v_mfma_f32_16x16x32_bf16 v[52:55], v[144:147], v[160:163], 0
	v_mfma_f32_16x16x32_bf16 v[48:51], v[152:155], v[160:163], 0
	v_mfma_f32_16x16x32_bf16 v[36:39], v[144:147], v[168:171], 0
	v_mfma_f32_16x16x32_bf16 v[28:31], v[152:155], v[168:171], 0
	v_mfma_f32_16x16x32_bf16 v[20:23], v[144:147], v[176:179], 0
	v_mfma_f32_16x16x32_bf16 v[12:15], v[152:155], v[176:179], 0
	v_mfma_f32_16x16x32_bf16 v[4:7], v[144:147], v[184:187], 0
	v_mfma_f32_16x16x32_bf16 v[0:3], v[152:155], v[184:187], 0
	v_mfma_f32_16x16x32_bf16 v[52:55], v[148:151], v[164:167], v[52:55]
	v_mfma_f32_16x16x32_bf16 v[48:51], v[156:159], v[164:167], v[48:51]
	v_mfma_f32_16x16x32_bf16 v[36:39], v[148:151], v[172:175], v[36:39]
	v_mfma_f32_16x16x32_bf16 v[28:31], v[156:159], v[172:175], v[28:31]
	v_mfma_f32_16x16x32_bf16 v[20:23], v[148:151], v[180:183], v[20:23]
	v_mfma_f32_16x16x32_bf16 v[12:15], v[156:159], v[180:183], v[12:15]
	v_mfma_f32_16x16x32_bf16 v[4:7], v[148:151], v[188:191], v[4:7]
	v_mfma_f32_16x16x32_bf16 v[0:3], v[156:159], v[188:191], v[0:3]
	s_setprio 0
	s_barrier
	s_add_i32 s52, 0, 0x18000
	s_add_i32 s53, 0, 0x1c000
	v_add_u32_e32 v140, s52, v247
	v_add_u32_e32 v156, s53, v247
	ds_read_b128 v[104:107], v140
	ds_read_b128 v[112:115], v140 offset:1024
	ds_read_b128 v[136:139], v140 offset:2048
	ds_read_b128 v[140:143], v140 offset:3072
	ds_read_b128 v[144:147], v156
	ds_read_b128 v[148:151], v156 offset:1024
	ds_read_b128 v[152:155], v156 offset:2048
	ds_read_b128 v[156:159], v156 offset:3072
	s_add_u32 s54, s54, 0x100000
	s_addc_u32 s55, s55, 0
	s_mov_b32 m0, s86
	v_lshl_add_u64 v[202:203], s[54:55], 0, v[218:219]
	ds_read_b128 v[160:163], v248 offset:32768
	ds_read_b128 v[164:167], v248 offset:33792
	ds_read_b128 v[168:171], v248 offset:34816
	ds_read_b128 v[172:175], v248 offset:35840
	ds_read_b128 v[176:179], v248 offset:36864
	ds_read_b128 v[180:183], v248 offset:37888
	ds_read_b128 v[184:187], v248 offset:38912
	ds_read_b128 v[188:191], v248 offset:39936
	global_load_lds_dwordx4 v[202:203], off
	v_lshl_add_u64 v[202:203], s[54:55], 0, v[214:215]
	s_mov_b32 m0, s66
	s_nop 0
	global_load_lds_dwordx4 v[202:203], off
	s_waitcnt vmcnt(8)
	s_waitcnt lgkmcnt(0)
	s_barrier
	s_setprio 1
	s_waitcnt lgkmcnt(0)
	v_mfma_f32_16x16x32_bf16 v[132:135], v[104:107], v[160:163], v[132:135]
	v_mfma_f32_16x16x32_bf16 v[128:131], v[136:139], v[160:163], v[128:131]
	v_mfma_f32_16x16x32_bf16 v[116:119], v[104:107], v[168:171], v[116:119]
	v_mfma_f32_16x16x32_bf16 v[108:111], v[136:139], v[168:171], v[108:111]
	v_mfma_f32_16x16x32_bf16 v[96:99], v[104:107], v[176:179], v[96:99]
	v_mfma_f32_16x16x32_bf16 v[88:91], v[136:139], v[176:179], v[88:91]
	v_mfma_f32_16x16x32_bf16 v[80:83], v[104:107], v[184:187], v[80:83]
	v_mfma_f32_16x16x32_bf16 v[72:75], v[136:139], v[184:187], v[72:75]
	v_mfma_f32_16x16x32_bf16 v[132:135], v[112:115], v[164:167], v[132:135]
	v_mfma_f32_16x16x32_bf16 v[128:131], v[140:143], v[164:167], v[128:131]
	v_mfma_f32_16x16x32_bf16 v[116:119], v[112:115], v[172:175], v[116:119]
	v_mfma_f32_16x16x32_bf16 v[108:111], v[140:143], v[172:175], v[108:111]
	v_mfma_f32_16x16x32_bf16 v[96:99], v[112:115], v[180:183], v[96:99]
	v_mfma_f32_16x16x32_bf16 v[88:91], v[140:143], v[180:183], v[88:91]
	v_mfma_f32_16x16x32_bf16 v[80:83], v[112:115], v[188:191], v[80:83]
	v_mfma_f32_16x16x32_bf16 v[72:75], v[140:143], v[188:191], v[72:75]
	s_setprio 0
	s_setprio 1
	v_mfma_f32_16x16x32_bf16 v[124:127], v[144:147], v[160:163], v[124:127]
	v_mfma_f32_16x16x32_bf16 v[120:123], v[152:155], v[160:163], v[120:123]
	v_mfma_f32_16x16x32_bf16 v[100:103], v[144:147], v[168:171], v[100:103]
	v_mfma_f32_16x16x32_bf16 v[92:95], v[152:155], v[168:171], v[92:95]
	v_mfma_f32_16x16x32_bf16 v[84:87], v[144:147], v[176:179], v[84:87]
	v_mfma_f32_16x16x32_bf16 v[76:79], v[152:155], v[176:179], v[76:79]
	v_mfma_f32_16x16x32_bf16 v[68:71], v[144:147], v[184:187], v[68:71]
	v_mfma_f32_16x16x32_bf16 v[64:67], v[152:155], v[184:187], v[64:67]
	v_mfma_f32_16x16x32_bf16 v[124:127], v[148:151], v[164:167], v[124:127]
	v_mfma_f32_16x16x32_bf16 v[120:123], v[156:159], v[164:167], v[120:123]
	v_mfma_f32_16x16x32_bf16 v[100:103], v[148:151], v[172:175], v[100:103]
	v_mfma_f32_16x16x32_bf16 v[92:95], v[156:159], v[172:175], v[92:95]
	v_mfma_f32_16x16x32_bf16 v[84:87], v[148:151], v[180:183], v[84:87]
	v_mfma_f32_16x16x32_bf16 v[76:79], v[156:159], v[180:183], v[76:79]
	v_mfma_f32_16x16x32_bf16 v[68:71], v[148:151], v[188:191], v[68:71]
	v_mfma_f32_16x16x32_bf16 v[64:67], v[156:159], v[188:191], v[64:67]
	s_setprio 0
	s_barrier
; #define PG8_STAGE(bufoff, gbase, voff) do { _Pragma("unroll") for (int _i = 0; _i < 2; ++_i) \
;         __builtin_amdgcn_global_load_lds((const unsigned*)((const char*)(gbase) + (voff)[_i]), (LAS unsigned*)(lds + (bufoff) + ldsw + _i * 8192), 16, 0, 0); } while (0)
; #define PG8_LDA(dst, b, h) do { _Pragma("unroll") for (int m = 0; m < 4; ++m) _Pragma("unroll") for (int k = 0; k < 2; ++k) dst[m][k] = *(const LAS bf16x8*)(lds + PG8_SA(b, h) + aoff + m * 2048 + k * 1024); } while (0)
; #define PG8_MMA(ai, bj, At, Bt) do { __builtin_amdgcn_s_setprio(1); _Pragma("unroll") for (int m = 0; m < 4; ++m) _Pragma("unroll") for (int n = 0; n < 2; ++n) _Pragma("unroll") for (int k = 0; k < 2; ++k) \
;         acc[ai][bj][m][n] = __builtin_amdgcn_mfma_f32_16x16x32_bf16(Bt[n][k], At[m][k], acc[ai][bj][m][n], 0, 0, 0); __builtin_amdgcn_s_setprio(0); } while (0)
; #define PG8_WAIT_V(n) asm volatile("s_waitcnt vmcnt(" #n ")" ::: "memory")
; #define PG8_WAIT_L(n) asm volatile("s_waitcnt lgkmcnt(" #n ")" ::: "memory")
; #define PG8_BAR __builtin_amdgcn_s_barrier()
; #define PG8_SCHED __builtin_amdgcn_sched_barrier(0)
; template <class Epi, class Sched, bool ALIGN_EPI>
; __device__ __forceinline__ void gemm_phase(LAS unsigned char* lds, const Gemm g, const Sched& S, const Epi& E) {
;     ...
;             const bool last = (t == nt - 2);
;             const char* a1 = cA + (size_t)(t + 1) * kstep;
;             const char* a2 = last ? nA : cA + (size_t)(t + 2) * kstep; const char* b2 = last ? nB : cB + (size_t)(t + 2) * kstep;
;             const char* a3 = a2 + kstep; const char* b3 = b2 + kstep;
;     ...
;             PG8_LDA(At, 1, 1); PG8_STAGE(PG8_SB(1, 0), b3, voffB); PG8_STAGE(PG8_SB(1, 1), b3 + hstepB, voffB); PG8_STAGE(PG8_SA(1, 0), a3, voffA);
;             PG8_WAIT_V(8); PG8_WAIT_L(0); PG8_BAR; PG8_MMA(1, 0, At, B0); PG8_MMA(1, 1, At, B1); PG8_BAR; PG8_SCHED;
	s_add_i32 s52, s52, s50
	v_lshl_add_u64 v[194:195], v[194:195], 0, s[12:13]
	s_mov_b32 m0, s52
	ds_read_b128 v[160:163], v248 offset:49152
	ds_read_b128 v[164:167], v248 offset:50176
	ds_read_b128 v[168:171], v248 offset:51200
	ds_read_b128 v[172:175], v248 offset:52224
	ds_read_b128 v[176:179], v248 offset:53248
	ds_read_b128 v[180:183], v248 offset:54272
	ds_read_b128 v[184:187], v248 offset:55296
	ds_read_b128 v[188:191], v248 offset:56320
	global_load_lds_dwordx4 v[194:195], off
	s_add_i32 m0, s52, 0x2000
	s_add_u32 s46, s46, 0x100080
	v_lshl_add_u64 v[194:195], v[196:197], 0, s[12:13]
	s_addc_u32 s47, s47, 0
	s_add_i32 s52, s53, s50
	global_load_lds_dwordx4 v[194:195], off
	v_lshl_add_u64 v[194:195], s[46:47], 0, v[216:217]
	s_mov_b32 m0, s52
	s_nop 0
	global_load_lds_dwordx4 v[194:195], off
	v_lshl_add_u64 v[194:195], s[46:47], 0, v[212:213]
	s_add_i32 m0, s52, 0x2000
	s_nop 0
	global_load_lds_dwordx4 v[194:195], off
	v_lshl_add_u64 v[194:195], v[198:199], 0, s[12:13]
	s_mov_b32 m0, s59
	s_nop 0
	global_load_lds_dwordx4 v[194:195], off
	v_lshl_add_u64 v[194:195], v[200:201], 0, s[12:13]
	s_mov_b32 m0, s4
	s_nop 0
	global_load_lds_dwordx4 v[194:195], off
	s_waitcnt vmcnt(8)
	s_waitcnt lgkmcnt(0)
	s_barrier
	s_setprio 1
	s_waitcnt lgkmcnt(0)
	v_mfma_f32_16x16x32_bf16 v[60:63], v[104:107], v[160:163], v[60:63]
	v_mfma_f32_16x16x32_bf16 v[56:59], v[136:139], v[160:163], v[56:59]
	v_mfma_f32_16x16x32_bf16 v[44:47], v[104:107], v[168:171], v[44:47]
	v_mfma_f32_16x16x32_bf16 v[40:43], v[136:139], v[168:171], v[40:43]
	v_mfma_f32_16x16x32_bf16 v[32:35], v[104:107], v[176:179], v[32:35]
	v_mfma_f32_16x16x32_bf16 v[24:27], v[136:139], v[176:179], v[24:27]
	v_mfma_f32_16x16x32_bf16 v[16:19], v[104:107], v[184:187], v[16:19]
	v_mfma_f32_16x16x32_bf16 v[8:11], v[136:139], v[184:187], v[8:11]
	v_mfma_f32_16x16x32_bf16 v[60:63], v[112:115], v[164:167], v[60:63]
	v_mfma_f32_16x16x32_bf16 v[56:59], v[140:143], v[164:167], v[56:59]
	v_mfma_f32_16x16x32_bf16 v[44:47], v[112:115], v[172:175], v[44:47]
	v_mfma_f32_16x16x32_bf16 v[40:43], v[140:143], v[172:175], v[40:43]
	v_mfma_f32_16x16x32_bf16 v[32:35], v[112:115], v[180:183], v[32:35]
	v_mfma_f32_16x16x32_bf16 v[24:27], v[140:143], v[180:183], v[24:27]
	v_mfma_f32_16x16x32_bf16 v[16:19], v[112:115], v[188:191], v[16:19]
	v_mfma_f32_16x16x32_bf16 v[8:11], v[140:143], v[188:191], v[8:11]
	s_setprio 0
	s_setprio 1
	v_mfma_f32_16x16x32_bf16 v[52:55], v[144:147], v[160:163], v[52:55]
	s_add_i32 s92, s92, 2
	v_mfma_f32_16x16x32_bf16 v[48:51], v[152:155], v[160:163], v[48:51]
	s_add_u32 s44, s44, 0x100
	v_mfma_f32_16x16x32_bf16 v[36:39], v[144:147], v[168:171], v[36:39]
	s_addc_u32 s45, s45, 0
	v_mfma_f32_16x16x32_bf16 v[28:31], v[152:155], v[168:171], v[28:31]
	s_add_u32 s65, s65, 0x100
	v_mfma_f32_16x16x32_bf16 v[20:23], v[144:147], v[176:179], v[20:23]
	s_addc_u32 s81, s81, 0
	v_mfma_f32_16x16x32_bf16 v[12:15], v[152:155], v[176:179], v[12:15]
	s_add_u32 s46, s44, 0xfff00080
	v_mfma_f32_16x16x32_bf16 v[4:7], v[144:147], v[184:187], v[4:7]
	s_addc_u32 s47, s45, -1
	v_mfma_f32_16x16x32_bf16 v[0:3], v[152:155], v[184:187], v[0:3]
	s_add_i32 s52, 0, 0x10000
	v_mfma_f32_16x16x32_bf16 v[52:55], v[148:151], v[164:167], v[52:55]
	s_cmp_eq_u32 s92, 60
	v_mfma_f32_16x16x32_bf16 v[48:51], v[156:159], v[164:167], v[48:51]
	s_cselect_b32 s55, s56, s47
	v_mfma_f32_16x16x32_bf16 v[36:39], v[148:151], v[172:175], v[36:39]
	s_cselect_b32 s54, s57, s46
	v_mfma_f32_16x16x32_bf16 v[28:31], v[156:159], v[172:175], v[28:31]
	s_cselect_b32 s47, s63, s81
	v_mfma_f32_16x16x32_bf16 v[20:23], v[148:151], v[180:183], v[20:23]
	s_cselect_b32 s46, s64, s65
	v_mfma_f32_16x16x32_bf16 v[12:15], v[156:159], v[180:183], v[12:15]
	s_add_i32 s53, 0, 0x14000
	v_mfma_f32_16x16x32_bf16 v[4:7], v[148:151], v[188:191], v[4:7]
	s_cmp_gt_u32 s92, 61
	v_mfma_f32_16x16x32_bf16 v[0:3], v[156:159], v[188:191], v[0:3]
	s_setprio 0
	s_barrier

; #define PG8_STAGE(bufoff, gbase, voff) do { _Pragma("unroll") for (int _i = 0; _i < 2; ++_i) \
;         __builtin_amdgcn_global_load_lds((const unsigned*)((const char*)(gbase) + (voff)[_i]), (LAS unsigned*)(lds + (bufoff) + ldsw + _i * 8192), 16, 0, 0); } while (0)
; #define PG8_WAIT_V(n) asm volatile("s_waitcnt vmcnt(" #n ")" ::: "memory")
; #define PG8_BAR __builtin_amdgcn_s_barrier()
; template <class Epi, class Sched, bool ALIGN_EPI>
; __device__ __forceinline__ void gemm_phase(LAS unsigned char* lds, const Gemm g, const Sched& S, const Epi& E) {
;     ...
;     const int wid = __builtin_amdgcn_readfirstlane(tid >> 6), lane = tid & 63, wr = wid >> 2, wc = wid & 3, fr = lane & 15, fq = lane >> 4;
;     const int K = g.K, nt = K / BK;
;     unsigned voffA[2], voffB[2];
; #pragma unroll
;     for (int i = 0; i < 2; ++i) { int R, C; stage_rc(tid * 16 + i * 8192, R, C); const int Rb = Epi::PERM ? ((R & ~31) + perm32(R & 31)) : R;
;         voffA[i] = (unsigned)(R * g.lda + C) * 2u; voffB[i] = (unsigned)(Rb * g.ldb + C) * 2u; }
;     const size_t kstep = (size_t)(BK * 2);
;     const size_t hstepA = (size_t)HALF * g.lda * 2, hstepB = (size_t)HALF * g.ldb * 2;
;     const size_t tstepA = 2 * hstepA, tstepB = 2 * hstepB;
;     const unsigned ldsw = (unsigned)wid * 1024u;
;     const int aoff = lds_byte(wr * 64 + fr, fq * 8), boff = lds_byte(wc * 32 + fr, fq * 8);
;     ...
;     Unit cur, nxt; int ui = 0;
;     if (!S.next(0, cur)) return;
;     f32x4 acc[2][2][4][2];
; #pragma unroll
;     for (int a = 0; a < 2; ++a)
; #pragma unroll
;         for (int b = 0; b < 2; ++b)
; #pragma unroll
;             for (int m = 0; m < 4; ++m)
; #pragma unroll
;                 for (int n = 0; n < 2; ++n) acc[a][b][m][n] = (f32x4){0.f, 0.f, 0.f, 0.f};
;     bf16x8 At[4][2], B0[2][2], B1[2][2];
;     const char* cA = (const char*)g.A + (size_t)cur.pm * tstepA; const char* cB = (const char*)g.Bt + (size_t)cur.pn * tstepB;
;     PG8_STAGE(PG8_SB(0, 0), cB, voffB); PG8_STAGE(PG8_SB(0, 1), cB + hstepB, voffB); PG8_STAGE(PG8_SA(0, 0), cA, voffA); PG8_STAGE(PG8_SA(0, 1), cA + hstepA, voffA);
;     if (wr == 1) PG8_BAR;
;     PG8_WAIT_V(2); PG8_BAR;
;     PG8_STAGE(PG8_SB(1, 0), cB + kstep, voffB); PG8_STAGE(PG8_SA(1, 0), cA + kstep, voffA); PG8_STAGE(PG8_SB(1, 1), cB + hstepB + kstep, voffB);
;     PG8_WAIT_V(6); PG8_BAR;
.LBB0_277:
	s_waitcnt lgkmcnt(0)
	s_add_u32 s6, s20, 0xe00000
	s_addc_u32 s7, s21, 0
	v_readlane_b32 s4, v255, 39
	v_readlane_b32 s5, v255, 40
	s_add_u32 s16, s16, s4
	s_addc_u32 s17, s17, s5
	s_add_u32 s59, s16, 0x500000
	s_addc_u32 s62, s17, 0
	v_bfe_u32 v159, v12, 4, 2
	s_add_u32 s8, s8, 0x10100000
	v_and_b32_e32 v158, 15, v12
	v_lshlrev_b32_e32 v15, 4, v159
	v_lshlrev_b32_e32 v12, 2, v12
	s_addc_u32 s9, s9, 0
	s_and_b32 s20, s38, 3
	v_lshl_or_b32 v15, v158, 6, v15
	s_lshl_b32 s16, s23, 13
	v_and_b32_e32 v12, 32, v12
	s_add_i32 m0, s53, 0x18000
	v_lshl_add_u64 v[4:5], v[4:5], 0, s[12:13]
	s_lshl_b32 s63, s23, 6
	v_bitop3_b32 v16, v15, s16, v12 bitop3:0xde
	s_lshl_b32 s64, s20, 5
	s_lshl_b32 s16, s20, 12
	s_waitcnt vmcnt(2)
	s_barrier
	global_load_lds_dwordx4 v[4:5], off
	v_lshl_add_u64 v[2:3], v[2:3], 0, s[12:13]
	s_add_i32 m0, s53, 0x1a000
	s_add_i32 s65, s53, 0x8000
	s_add_i32 s66, s53, 0xa000
	v_bitop3_b32 v160, v15, s16, v12 bitop3:0xde
	global_load_lds_dwordx4 v[2:3], off
	v_lshl_add_u64 v[0:1], v[0:1], 0, s[12:13]
	s_mov_b32 m0, s65
	s_add_u32 s16, s46, 0x40080
	global_load_lds_dwordx4 v[0:1], off
	v_lshl_add_u64 v[0:1], v[6:7], 0, s[12:13]
	s_mov_b32 m0, s66
	s_addc_u32 s17, s47, 0
	global_load_lds_dwordx4 v[0:1], off
	s_add_i32 m0, s53, 0x1c000
	v_lshl_add_u64 v[0:1], s[16:17], 0, v[192:193]
	global_load_lds_dwordx4 v[0:1], off
	v_lshl_add_u64 v[0:1], s[16:17], 0, v[144:145]
	s_add_i32 m0, s53, 0x1e000
	s_cmpk_lt_u32 s22, 0x100
	global_load_lds_dwordx4 v[0:1], off
	v_lshlrev_b32_e32 v0, 14, v13
	v_and_b32_e32 v0, 0xffff8000, v0
	v_lshl_add_u32 v0, v11, 11, v0
	v_and_b32_e32 v1, 1, v13
	v_lshl_or_b32 v0, v1, 6, v0
	v_lshl_add_u32 v150, v14, 1, v0
	v_lshlrev_b32_e32 v0, 14, v8
	s_cselect_b64 s[16:17], -1, 0
	s_and_b32 s21, s22, 0xffffff00
	s_lshl_b32 s20, s20, 6
	v_and_b32_e32 v0, 0xffff8000, v0
	s_waitcnt vmcnt(0)
	s_or_b32 s67, s20, s21
	s_lshl_b32 s20, s23, 8
	v_lshl_add_u32 v0, v9, 11, v0
	v_and_b32_e32 v1, 1, v8
	s_add_i32 s77, s20, 0
	v_lshl_or_b32 v0, v1, 6, v0
	v_readlane_b32 s4, v254, 37
	s_add_i32 s76, s77, 0x20000
	s_add_i32 s77, s77, 0x20200
	v_mov_b32_e32 v151, v193
	v_lshl_add_u32 v152, v10, 1, v0
	v_mov_b32_e32 v153, v193
	s_mov_b32 s80, 0
	v_add_u32_e32 v161, 0, v16
	v_readlane_b32 s84, v254, 24
	s_mov_b32 s81, s4
	s_barrier
	v_readlane_b32 s5, v254, 38
	s_branch .LBB0_280

; #define PG8_STAGE(bufoff, gbase, voff) do { _Pragma("unroll") for (int _i = 0; _i < 2; ++_i) \
;         __builtin_amdgcn_global_load_lds((const unsigned*)((const char*)(gbase) + (voff)[_i]), (LAS unsigned*)(lds + (bufoff) + ldsw + _i * 8192), 16, 0, 0); } while (0)
; #define PG8_LDA(dst, b, h) do { _Pragma("unroll") for (int m = 0; m < 4; ++m) _Pragma("unroll") for (int k = 0; k < 2; ++k) dst[m][k] = *(const LAS bf16x8*)(lds + PG8_SA(b, h) + aoff + m * 2048 + k * 1024); } while (0)
; #define PG8_LDB(dst, b, h) do { _Pragma("unroll") for (int n = 0; n < 2; ++n) _Pragma("unroll") for (int k = 0; k < 2; ++k) dst[n][k] = *(const LAS bf16x8*)(lds + PG8_SB(b, h) + boff + n * 2048 + k * 1024); } while (0)
; #define PG8_MMA(ai, bj, At, Bt) do { __builtin_amdgcn_s_setprio(1); _Pragma("unroll") for (int m = 0; m < 4; ++m) _Pragma("unroll") for (int n = 0; n < 2; ++n) _Pragma("unroll") for (int k = 0; k < 2; ++k) \
;         acc[ai][bj][m][n] = __builtin_amdgcn_mfma_f32_16x16x32_bf16(Bt[n][k], At[m][k], acc[ai][bj][m][n], 0, 0, 0); __builtin_amdgcn_s_setprio(0); } while (0)
; #define PG8_WAIT_V(n) asm volatile("s_waitcnt vmcnt(" #n ")" ::: "memory")
; #define PG8_WAIT_L(n) asm volatile("s_waitcnt lgkmcnt(" #n ")" ::: "memory")
; template <class Epi, class Sched, bool ALIGN_EPI>
; __device__ __forceinline__ void gemm_phase(LAS unsigned char* lds, const Gemm g, const Sched& S, const Epi& E) {
;     ...
;         const bool has_next = S.next(ui + 1, nxt);
;         const char* nA = has_next ? (const char*)g.A + (size_t)nxt.pm * tstepA : cA; const char* nB = has_next ? (const char*)g.Bt + (size_t)nxt.pn * tstepB : cB;
;         for (int t = 0; t < nt; t += 2) {
;             const bool last = (t == nt - 2);
;             const char* a1 = cA + (size_t)(t + 1) * kstep;
;             const char* a2 = last ? nA : cA + (size_t)(t + 2) * kstep; const char* b2 = last ? nB : cB + (size_t)(t + 2) * kstep;
;             const char* a3 = a2 + kstep; const char* b3 = b2 + kstep;
;             PG8_LDB(B0, 0, 0); PG8_LDB(B1, 0, 1); PG8_SCHED; PG8_LDA(At, 0, 0); PG8_STAGE(PG8_SA(1, 1), a1 + hstepA, voffA);
;             PG8_WAIT_V(8); PG8_WAIT_L(0); PG8_BAR; PG8_MMA(0, 0, At, B0); PG8_MMA(0, 1, At, B1); PG8_BAR; PG8_SCHED;
;             PG8_LDA(At, 0, 1); PG8_STAGE(PG8_SB(0, 0), b2, voffB); PG8_STAGE(PG8_SB(0, 1), b2 + hstepB, voffB); PG8_STAGE(PG8_SA(0, 0), a2, voffA);
.LBB0_286:
	s_ashr_i32 s23, s22, 31
	s_lshl_b64 s[38:39], s[22:23], 19
	s_add_u32 s38, s48, s38
	s_addc_u32 s39, s49, s39
	s_and_b64 s[40:41], s[42:43], exec
	s_cselect_b32 s23, s39, s45
	s_cselect_b32 s85, s38, s44
	s_ashr_i32 s21, s20, 31
	s_lshl_b64 s[40:41], s[20:21], 19
	s_add_u32 s40, s50, s40
	s_addc_u32 s41, s51, s41
	s_and_b64 s[54:55], s[42:43], exec
	s_cselect_b32 s21, s41, s47
	s_cselect_b32 s86, s40, s46
	s_add_u32 s44, s44, 0x40080
	s_addc_u32 s45, s45, 0
	s_add_u32 s87, s46, 0x100
	s_addc_u32 s90, s47, 0
	s_mov_b32 s91, -2
	s_add_u32 s46, s44, 0xfffc0080
	s_addc_u32 s47, s45, -1
	s_add_i32 s92, 0, 0x10000
	s_cmp_eq_u32 s91, 12
	s_cselect_b32 s55, s23, s47
	s_cselect_b32 s54, s85, s46
	s_cselect_b32 s47, s21, s90
	s_cselect_b32 s46, s86, s87
	s_add_i32 s4, 0, 0x14000
	v_add_u32_e32 v132, s92, v160
	v_add_u32_e32 v170, s4, v160
	ds_read_b128 v[120:123], v132
	ds_read_b128 v[124:127], v132 offset:1024
	ds_read_b128 v[128:131], v132 offset:2048
	ds_read_b128 v[132:135], v132 offset:3072
	ds_read_b128 v[154:157], v170
	ds_read_b128 v[162:165], v170 offset:1024
	ds_read_b128 v[166:169], v170 offset:2048
	ds_read_b128 v[170:173], v170 offset:3072
	v_lshl_add_u64 v[190:191], s[44:45], 0, v[150:151]
	s_add_i32 m0, s53, 0xc000
	ds_read_b128 v[174:177], v161
	ds_read_b128 v[178:181], v161 offset:1024
	ds_read_b128 v[182:185], v161 offset:2048
	ds_read_b128 v[186:189], v161 offset:3072
	ds_read_b128 v[194:197], v161 offset:4096
	ds_read_b128 v[198:201], v161 offset:5120
	ds_read_b128 v[202:205], v161 offset:6144
	ds_read_b128 v[212:215], v161 offset:7168
	global_load_lds_dwordx4 v[190:191], off
	v_lshl_add_u64 v[190:191], s[44:45], 0, v[152:153]
	s_add_i32 m0, s53, 0xe000
	s_nop 0
	global_load_lds_dwordx4 v[190:191], off
	s_waitcnt lgkmcnt(0)
	s_barrier
	s_setprio 1
	s_waitcnt lgkmcnt(0)
	v_mfma_f32_16x16x32_bf16 v[140:143], v[120:123], v[174:177], 0
	v_mfma_f32_16x16x32_bf16 v[136:139], v[128:131], v[174:177], 0
	v_mfma_f32_16x16x32_bf16 v[108:111], v[120:123], v[182:185], 0
	v_mfma_f32_16x16x32_bf16 v[104:107], v[128:131], v[182:185], 0
	v_mfma_f32_16x16x32_bf16 v[92:95], v[120:123], v[194:197], 0
	v_mfma_f32_16x16x32_bf16 v[88:91], v[128:131], v[194:197], 0
	v_mfma_f32_16x16x32_bf16 v[76:79], v[120:123], v[202:205], 0
	v_mfma_f32_16x16x32_bf16 v[72:75], v[128:131], v[202:205], 0
	v_mfma_f32_16x16x32_bf16 v[140:143], v[124:127], v[178:181], v[140:143]
	v_mfma_f32_16x16x32_bf16 v[136:139], v[132:135], v[178:181], v[136:139]
	v_mfma_f32_16x16x32_bf16 v[108:111], v[124:127], v[186:189], v[108:111]
	v_mfma_f32_16x16x32_bf16 v[104:107], v[132:135], v[186:189], v[104:107]
	v_mfma_f32_16x16x32_bf16 v[92:95], v[124:127], v[198:201], v[92:95]
	v_mfma_f32_16x16x32_bf16 v[88:91], v[132:135], v[198:201], v[88:91]
	v_mfma_f32_16x16x32_bf16 v[76:79], v[124:127], v[212:215], v[76:79]
	v_mfma_f32_16x16x32_bf16 v[72:75], v[132:135], v[212:215], v[72:75]
	s_setprio 0
	s_setprio 1
	v_mfma_f32_16x16x32_bf16 v[116:119], v[154:157], v[174:177], 0
	v_mfma_f32_16x16x32_bf16 v[112:115], v[166:169], v[174:177], 0
	v_mfma_f32_16x16x32_bf16 v[100:103], v[154:157], v[182:185], 0
	v_mfma_f32_16x16x32_bf16 v[96:99], v[166:169], v[182:185], 0
	v_mfma_f32_16x16x32_bf16 v[84:87], v[154:157], v[194:197], 0
	v_mfma_f32_16x16x32_bf16 v[80:83], v[166:169], v[194:197], 0
	v_mfma_f32_16x16x32_bf16 v[68:71], v[154:157], v[202:205], 0
	v_mfma_f32_16x16x32_bf16 v[64:67], v[166:169], v[202:205], 0
	v_mfma_f32_16x16x32_bf16 v[116:119], v[162:165], v[178:181], v[116:119]
	v_mfma_f32_16x16x32_bf16 v[112:115], v[170:173], v[178:181], v[112:115]
	v_mfma_f32_16x16x32_bf16 v[100:103], v[162:165], v[186:189], v[100:103]
	v_mfma_f32_16x16x32_bf16 v[96:99], v[170:173], v[186:189], v[96:99]
	v_mfma_f32_16x16x32_bf16 v[84:87], v[162:165], v[198:201], v[84:87]
	v_mfma_f32_16x16x32_bf16 v[80:83], v[170:173], v[198:201], v[80:83]
	v_mfma_f32_16x16x32_bf16 v[68:71], v[162:165], v[212:215], v[68:71]
	v_mfma_f32_16x16x32_bf16 v[64:67], v[170:173], v[212:215], v[64:67]
	s_setprio 0
	s_barrier
	s_add_i32 s5, s92, s52
	v_lshl_add_u64 v[190:191], s[46:47], 0, v[192:193]
	s_mov_b32 m0, s5
	ds_read_b128 v[174:177], v161 offset:16384
	ds_read_b128 v[178:181], v161 offset:17408
	ds_read_b128 v[182:185], v161 offset:18432
	ds_read_b128 v[186:189], v161 offset:19456
	ds_read_b128 v[194:197], v161 offset:20480
	ds_read_b128 v[198:201], v161 offset:21504
	ds_read_b128 v[202:205], v161 offset:22528
	ds_read_b128 v[212:215], v161 offset:23552
	global_load_lds_dwordx4 v[190:191], off
	s_add_i32 m0, s5, 0x2000
	s_add_u32 vcc_lo, s46, 0x40000
	v_lshl_add_u64 v[216:217], s[46:47], 0, v[144:145]
	s_addc_u32 vcc_hi, s47, 0
	s_add_i32 s4, s4, s52
	global_load_lds_dwordx4 v[216:217], off
	v_lshl_add_u64 v[218:219], vcc, 0, v[192:193]
	s_mov_b32 m0, s4
	v_lshl_add_u64 v[220:221], s[54:55], 0, v[146:147]
	global_load_lds_dwordx4 v[218:219], off
	v_lshl_add_u64 v[218:219], vcc, 0, v[144:145]
	s_add_i32 m0, s4, 0x2000
	s_nop 0
	global_load_lds_dwordx4 v[218:219], off
	v_lshl_add_u64 v[218:219], s[54:55], 0, v[148:149]
	s_mov_b32 m0, s53
	s_nop 0
	global_load_lds_dwordx4 v[218:219], off
	s_mov_b32 m0, s56
	s_nop 0
	global_load_lds_dwordx4 v[220:221], off
	s_waitcnt lgkmcnt(0)
	s_barrier
; #define PG8_STAGE(bufoff, gbase, voff) do { _Pragma("unroll") for (int _i = 0; _i < 2; ++_i) \
;         __builtin_amdgcn_global_load_lds((const unsigned*)((const char*)(gbase) + (voff)[_i]), (LAS unsigned*)(lds + (bufoff) + ldsw + _i * 8192), 16, 0, 0); } while (0)
; #define PG8_LDA(dst, b, h) do { _Pragma("unroll") for (int m = 0; m < 4; ++m) _Pragma("unroll") for (int k = 0; k < 2; ++k) dst[m][k] = *(const LAS bf16x8*)(lds + PG8_SA(b, h) + aoff + m * 2048 + k * 1024); } while (0)
; #define PG8_LDB(dst, b, h) do { _Pragma("unroll") for (int n = 0; n < 2; ++n) _Pragma("unroll") for (int k = 0; k < 2; ++k) dst[n][k] = *(const LAS bf16x8*)(lds + PG8_SB(b, h) + boff + n * 2048 + k * 1024); } while (0)
; #define PG8_MMA(ai, bj, At, Bt) do { __builtin_amdgcn_s_setprio(1); _Pragma("unroll") for (int m = 0; m < 4; ++m) _Pragma("unroll") for (int n = 0; n < 2; ++n) _Pragma("unroll") for (int k = 0; k < 2; ++k) \
;         acc[ai][bj][m][n] = __builtin_amdgcn_mfma_f32_16x16x32_bf16(Bt[n][k], At[m][k], acc[ai][bj][m][n], 0, 0, 0); __builtin_amdgcn_s_setprio(0); } while (0)
; #define PG8_WAIT_V(n) asm volatile("s_waitcnt vmcnt(" #n ")" ::: "memory")
; #define PG8_WAIT_L(n) asm volatile("s_waitcnt lgkmcnt(" #n ")" ::: "memory")
; #define PG8_BAR __builtin_amdgcn_s_barrier()
; #define PG8_SCHED __builtin_amdgcn_sched_barrier(0)
; template <class Epi, class Sched, bool ALIGN_EPI>
; __device__ __forceinline__ void gemm_phase(LAS unsigned char* lds, const Gemm g, const Sched& S, const Epi& E) {
;     ...
;             PG8_WAIT_V(8); PG8_WAIT_L(0); PG8_BAR; PG8_MMA(1, 0, At, B0); PG8_MMA(1, 1, At, B1); PG8_BAR; PG8_SCHED;
;             PG8_LDB(B0, 1, 0); PG8_LDB(B1, 1, 1); PG8_SCHED; PG8_LDA(At, 1, 0); PG8_STAGE(PG8_SA(0, 1), a2 + hstepA, voffA);
;             PG8_WAIT_V(8); PG8_WAIT_L(0); PG8_BAR; PG8_MMA(0, 0, At, B0); PG8_MMA(0, 1, At, B1); PG8_BAR; PG8_SCHED;
	s_setprio 1
	s_waitcnt lgkmcnt(0)
	v_mfma_f32_16x16x32_bf16 v[60:63], v[120:123], v[174:177], 0
	v_mfma_f32_16x16x32_bf16 v[56:59], v[128:131], v[174:177], 0
	v_mfma_f32_16x16x32_bf16 v[48:51], v[120:123], v[182:185], 0
	v_mfma_f32_16x16x32_bf16 v[40:43], v[128:131], v[182:185], 0
	v_mfma_f32_16x16x32_bf16 v[32:35], v[120:123], v[194:197], 0
	v_mfma_f32_16x16x32_bf16 v[24:27], v[128:131], v[194:197], 0
	v_mfma_f32_16x16x32_bf16 v[16:19], v[120:123], v[202:205], 0
	v_mfma_f32_16x16x32_bf16 v[8:11], v[128:131], v[202:205], 0
	v_mfma_f32_16x16x32_bf16 v[60:63], v[124:127], v[178:181], v[60:63]
	v_mfma_f32_16x16x32_bf16 v[56:59], v[132:135], v[178:181], v[56:59]
	v_mfma_f32_16x16x32_bf16 v[48:51], v[124:127], v[186:189], v[48:51]
	v_mfma_f32_16x16x32_bf16 v[40:43], v[132:135], v[186:189], v[40:43]
	v_mfma_f32_16x16x32_bf16 v[32:35], v[124:127], v[198:201], v[32:35]
	v_mfma_f32_16x16x32_bf16 v[24:27], v[132:135], v[198:201], v[24:27]
	v_mfma_f32_16x16x32_bf16 v[16:19], v[124:127], v[212:215], v[16:19]
	v_mfma_f32_16x16x32_bf16 v[8:11], v[132:135], v[212:215], v[8:11]
	s_setprio 0
	s_setprio 1
	v_mfma_f32_16x16x32_bf16 v[52:55], v[154:157], v[174:177], 0
	v_mfma_f32_16x16x32_bf16 v[44:47], v[166:169], v[174:177], 0
	v_mfma_f32_16x16x32_bf16 v[36:39], v[154:157], v[182:185], 0
	v_mfma_f32_16x16x32_bf16 v[28:31], v[166:169], v[182:185], 0
	v_mfma_f32_16x16x32_bf16 v[20:23], v[154:157], v[194:197], 0
	v_mfma_f32_16x16x32_bf16 v[12:15], v[166:169], v[194:197], 0
	v_mfma_f32_16x16x32_bf16 v[4:7], v[154:157], v[202:205], 0
	v_mfma_f32_16x16x32_bf16 v[0:3], v[166:169], v[202:205], 0
	v_mfma_f32_16x16x32_bf16 v[52:55], v[162:165], v[178:181], v[52:55]
	v_mfma_f32_16x16x32_bf16 v[44:47], v[170:173], v[178:181], v[44:47]
	v_mfma_f32_16x16x32_bf16 v[36:39], v[162:165], v[186:189], v[36:39]
	v_mfma_f32_16x16x32_bf16 v[28:31], v[170:173], v[186:189], v[28:31]
	v_mfma_f32_16x16x32_bf16 v[20:23], v[162:165], v[198:201], v[20:23]
	v_mfma_f32_16x16x32_bf16 v[12:15], v[170:173], v[198:201], v[12:15]
	v_mfma_f32_16x16x32_bf16 v[4:7], v[162:165], v[212:215], v[4:7]
	v_mfma_f32_16x16x32_bf16 v[0:3], v[170:173], v[212:215], v[0:3]
	s_setprio 0
	s_barrier
	s_add_i32 s4, 0, 0x18000
	s_add_i32 s5, 0, 0x1c000
	v_add_u32_e32 v132, s4, v160
	v_add_u32_e32 v170, s5, v160
	ds_read_b128 v[120:123], v132
	ds_read_b128 v[124:127], v132 offset:1024
	ds_read_b128 v[128:131], v132 offset:2048
	ds_read_b128 v[132:135], v132 offset:3072
	ds_read_b128 v[154:157], v170
	ds_read_b128 v[162:165], v170 offset:1024
	ds_read_b128 v[166:169], v170 offset:2048
	ds_read_b128 v[170:173], v170 offset:3072
	s_add_u32 s54, s54, 0x40000
	s_addc_u32 s55, s55, 0
	s_mov_b32 m0, s57
	v_lshl_add_u64 v[222:223], s[54:55], 0, v[148:149]
	ds_read_b128 v[174:177], v161 offset:32768
	ds_read_b128 v[178:181], v161 offset:33792
	ds_read_b128 v[182:185], v161 offset:34816
	ds_read_b128 v[186:189], v161 offset:35840
	ds_read_b128 v[194:197], v161 offset:36864
	ds_read_b128 v[198:201], v161 offset:37888
	ds_read_b128 v[202:205], v161 offset:38912
	ds_read_b128 v[212:215], v161 offset:39936
	global_load_lds_dwordx4 v[222:223], off
	v_lshl_add_u64 v[222:223], s[54:55], 0, v[146:147]
	s_mov_b32 m0, s58
	s_nop 0
	global_load_lds_dwordx4 v[222:223], off
	s_waitcnt vmcnt(8)
	s_waitcnt lgkmcnt(0)
	s_barrier
	s_setprio 1
	s_waitcnt lgkmcnt(0)
	v_mfma_f32_16x16x32_bf16 v[140:143], v[120:123], v[174:177], v[140:143]
	v_mfma_f32_16x16x32_bf16 v[136:139], v[128:131], v[174:177], v[136:139]
	v_mfma_f32_16x16x32_bf16 v[108:111], v[120:123], v[182:185], v[108:111]
	v_mfma_f32_16x16x32_bf16 v[104:107], v[128:131], v[182:185], v[104:107]
	v_mfma_f32_16x16x32_bf16 v[92:95], v[120:123], v[194:197], v[92:95]
	v_mfma_f32_16x16x32_bf16 v[88:91], v[128:131], v[194:197], v[88:91]
	v_mfma_f32_16x16x32_bf16 v[76:79], v[120:123], v[202:205], v[76:79]
	v_mfma_f32_16x16x32_bf16 v[72:75], v[128:131], v[202:205], v[72:75]
	v_mfma_f32_16x16x32_bf16 v[140:143], v[124:127], v[178:181], v[140:143]
	v_mfma_f32_16x16x32_bf16 v[136:139], v[132:135], v[178:181], v[136:139]
	v_mfma_f32_16x16x32_bf16 v[108:111], v[124:127], v[186:189], v[108:111]
	v_mfma_f32_16x16x32_bf16 v[104:107], v[132:135], v[186:189], v[104:107]
	v_mfma_f32_16x16x32_bf16 v[92:95], v[124:127], v[198:201], v[92:95]
	v_mfma_f32_16x16x32_bf16 v[88:91], v[132:135], v[198:201], v[88:91]
	v_mfma_f32_16x16x32_bf16 v[76:79], v[124:127], v[212:215], v[76:79]
	v_mfma_f32_16x16x32_bf16 v[72:75], v[132:135], v[212:215], v[72:75]
	s_setprio 0
	s_setprio 1
	v_mfma_f32_16x16x32_bf16 v[116:119], v[154:157], v[174:177], v[116:119]
	v_mfma_f32_16x16x32_bf16 v[112:115], v[166:169], v[174:177], v[112:115]
	v_mfma_f32_16x16x32_bf16 v[100:103], v[154:157], v[182:185], v[100:103]
	v_mfma_f32_16x16x32_bf16 v[96:99], v[166:169], v[182:185], v[96:99]
	v_mfma_f32_16x16x32_bf16 v[84:87], v[154:157], v[194:197], v[84:87]
	v_mfma_f32_16x16x32_bf16 v[80:83], v[166:169], v[194:197], v[80:83]
	v_mfma_f32_16x16x32_bf16 v[68:71], v[154:157], v[202:205], v[68:71]
	v_mfma_f32_16x16x32_bf16 v[64:67], v[166:169], v[202:205], v[64:67]
	v_mfma_f32_16x16x32_bf16 v[116:119], v[162:165], v[178:181], v[116:119]
	v_mfma_f32_16x16x32_bf16 v[112:115], v[170:173], v[178:181], v[112:115]
	v_mfma_f32_16x16x32_bf16 v[100:103], v[162:165], v[186:189], v[100:103]
	v_mfma_f32_16x16x32_bf16 v[96:99], v[170:173], v[186:189], v[96:99]
	v_mfma_f32_16x16x32_bf16 v[84:87], v[162:165], v[198:201], v[84:87]
	v_mfma_f32_16x16x32_bf16 v[80:83], v[170:173], v[198:201], v[80:83]
	v_mfma_f32_16x16x32_bf16 v[68:71], v[162:165], v[212:215], v[68:71]
	v_mfma_f32_16x16x32_bf16 v[64:67], v[170:173], v[212:215], v[64:67]
	s_setprio 0
	s_barrier
; #define PG8_STAGE(bufoff, gbase, voff) do { _Pragma("unroll") for (int _i = 0; _i < 2; ++_i) \
;         __builtin_amdgcn_global_load_lds((const unsigned*)((const char*)(gbase) + (voff)[_i]), (LAS unsigned*)(lds + (bufoff) + ldsw + _i * 8192), 16, 0, 0); } while (0)
; #define PG8_LDA(dst, b, h) do { _Pragma("unroll") for (int m = 0; m < 4; ++m) _Pragma("unroll") for (int k = 0; k < 2; ++k) dst[m][k] = *(const LAS bf16x8*)(lds + PG8_SA(b, h) + aoff + m * 2048 + k * 1024); } while (0)
; #define PG8_MMA(ai, bj, At, Bt) do { __builtin_amdgcn_s_setprio(1); _Pragma("unroll") for (int m = 0; m < 4; ++m) _Pragma("unroll") for (int n = 0; n < 2; ++n) _Pragma("unroll") for (int k = 0; k < 2; ++k) \
;         acc[ai][bj][m][n] = __builtin_amdgcn_mfma_f32_16x16x32_bf16(Bt[n][k], At[m][k], acc[ai][bj][m][n], 0, 0, 0); __builtin_amdgcn_s_setprio(0); } while (0)
; #define PG8_WAIT_V(n) asm volatile("s_waitcnt vmcnt(" #n ")" ::: "memory")
; #define PG8_WAIT_L(n) asm volatile("s_waitcnt lgkmcnt(" #n ")" ::: "memory")
; #define PG8_BAR __builtin_amdgcn_s_barrier()
; #define PG8_SCHED __builtin_amdgcn_sched_barrier(0)
; template <class Epi, class Sched, bool ALIGN_EPI>
; __device__ __forceinline__ void gemm_phase(LAS unsigned char* lds, const Gemm g, const Sched& S, const Epi& E) {
;     ...
;             const bool last = (t == nt - 2);
;             const char* a1 = cA + (size_t)(t + 1) * kstep;
;             const char* a2 = last ? nA : cA + (size_t)(t + 2) * kstep; const char* b2 = last ? nB : cB + (size_t)(t + 2) * kstep;
;             const char* a3 = a2 + kstep; const char* b3 = b2 + kstep;
;     ...
;             PG8_LDA(At, 1, 1); PG8_STAGE(PG8_SB(1, 0), b3, voffB); PG8_STAGE(PG8_SB(1, 1), b3 + hstepB, voffB); PG8_STAGE(PG8_SA(1, 0), a3, voffA);
;             PG8_WAIT_V(8); PG8_WAIT_L(0); PG8_BAR; PG8_MMA(1, 0, At, B0); PG8_MMA(1, 1, At, B1); PG8_BAR; PG8_SCHED;
	s_add_i32 s4, s4, s52
	v_lshl_add_u64 v[190:191], v[190:191], 0, s[12:13]
	s_mov_b32 m0, s4
	ds_read_b128 v[174:177], v161 offset:49152
	ds_read_b128 v[178:181], v161 offset:50176
	ds_read_b128 v[182:185], v161 offset:51200
	ds_read_b128 v[186:189], v161 offset:52224
	ds_read_b128 v[194:197], v161 offset:53248
	ds_read_b128 v[198:201], v161 offset:54272
	ds_read_b128 v[202:205], v161 offset:55296
	ds_read_b128 v[212:215], v161 offset:56320
	global_load_lds_dwordx4 v[190:191], off
	s_add_i32 m0, s4, 0x2000
	s_add_u32 s46, s46, 0x40080
	v_lshl_add_u64 v[190:191], v[216:217], 0, s[12:13]
	s_addc_u32 s47, s47, 0
	s_add_i32 s4, s5, s52
	global_load_lds_dwordx4 v[190:191], off
	v_lshl_add_u64 v[190:191], s[46:47], 0, v[192:193]
	s_mov_b32 m0, s4
	s_nop 0
	global_load_lds_dwordx4 v[190:191], off
	v_lshl_add_u64 v[190:191], s[46:47], 0, v[144:145]
	s_add_i32 m0, s4, 0x2000
	s_nop 0
	global_load_lds_dwordx4 v[190:191], off
	v_lshl_add_u64 v[190:191], v[218:219], 0, s[12:13]
	s_mov_b32 m0, s65
	s_nop 0
	global_load_lds_dwordx4 v[190:191], off
	v_lshl_add_u64 v[190:191], v[220:221], 0, s[12:13]
	s_mov_b32 m0, s66
	s_nop 0
	global_load_lds_dwordx4 v[190:191], off
	s_waitcnt vmcnt(8)
	s_waitcnt lgkmcnt(0)
	s_barrier
	s_setprio 1
	s_waitcnt lgkmcnt(0)
	v_mfma_f32_16x16x32_bf16 v[60:63], v[120:123], v[174:177], v[60:63]
	v_mfma_f32_16x16x32_bf16 v[56:59], v[128:131], v[174:177], v[56:59]
	v_mfma_f32_16x16x32_bf16 v[48:51], v[120:123], v[182:185], v[48:51]
	v_mfma_f32_16x16x32_bf16 v[40:43], v[128:131], v[182:185], v[40:43]
	v_mfma_f32_16x16x32_bf16 v[32:35], v[120:123], v[194:197], v[32:35]
	v_mfma_f32_16x16x32_bf16 v[24:27], v[128:131], v[194:197], v[24:27]
	v_mfma_f32_16x16x32_bf16 v[16:19], v[120:123], v[202:205], v[16:19]
	v_mfma_f32_16x16x32_bf16 v[8:11], v[128:131], v[202:205], v[8:11]
	v_mfma_f32_16x16x32_bf16 v[60:63], v[124:127], v[178:181], v[60:63]
	v_mfma_f32_16x16x32_bf16 v[56:59], v[132:135], v[178:181], v[56:59]
	v_mfma_f32_16x16x32_bf16 v[48:51], v[124:127], v[186:189], v[48:51]
	v_mfma_f32_16x16x32_bf16 v[40:43], v[132:135], v[186:189], v[40:43]
	v_mfma_f32_16x16x32_bf16 v[32:35], v[124:127], v[198:201], v[32:35]
	v_mfma_f32_16x16x32_bf16 v[24:27], v[132:135], v[198:201], v[24:27]
	v_mfma_f32_16x16x32_bf16 v[16:19], v[124:127], v[212:215], v[16:19]
	v_mfma_f32_16x16x32_bf16 v[8:11], v[132:135], v[212:215], v[8:11]
	s_setprio 0
	s_setprio 1
	v_mfma_f32_16x16x32_bf16 v[52:55], v[154:157], v[174:177], v[52:55]
	s_add_i32 s91, s91, 2
	v_mfma_f32_16x16x32_bf16 v[44:47], v[166:169], v[174:177], v[44:47]
	s_add_u32 s44, s44, 0x100
	v_mfma_f32_16x16x32_bf16 v[36:39], v[154:157], v[182:185], v[36:39]
	s_addc_u32 s45, s45, 0
	v_mfma_f32_16x16x32_bf16 v[28:31], v[166:169], v[182:185], v[28:31]
	s_add_u32 s87, s87, 0x100
	v_mfma_f32_16x16x32_bf16 v[20:23], v[154:157], v[194:197], v[20:23]
	s_addc_u32 s90, s90, 0
	v_mfma_f32_16x16x32_bf16 v[12:15], v[166:169], v[194:197], v[12:15]
	s_add_u32 s46, s44, 0xfffc0080
	v_mfma_f32_16x16x32_bf16 v[4:7], v[154:157], v[202:205], v[4:7]
	s_addc_u32 s47, s45, -1
	v_mfma_f32_16x16x32_bf16 v[0:3], v[166:169], v[202:205], v[0:3]
	s_add_i32 s92, 0, 0x10000
	v_mfma_f32_16x16x32_bf16 v[52:55], v[162:165], v[178:181], v[52:55]
	s_cmp_eq_u32 s91, 12
	v_mfma_f32_16x16x32_bf16 v[44:47], v[170:173], v[178:181], v[44:47]
	s_cselect_b32 s55, s23, s47
	v_mfma_f32_16x16x32_bf16 v[36:39], v[162:165], v[186:189], v[36:39]
	s_cselect_b32 s54, s85, s46
	v_mfma_f32_16x16x32_bf16 v[28:31], v[170:173], v[186:189], v[28:31]
	s_cselect_b32 s47, s21, s90
	v_mfma_f32_16x16x32_bf16 v[20:23], v[162:165], v[198:201], v[20:23]
	s_cselect_b32 s46, s86, s87
	v_mfma_f32_16x16x32_bf16 v[12:15], v[170:173], v[198:201], v[12:15]
	s_add_i32 s4, 0, 0x14000
	v_mfma_f32_16x16x32_bf16 v[4:7], v[162:165], v[212:215], v[4:7]
	s_cmp_gt_u32 s91, 13
	v_mfma_f32_16x16x32_bf16 v[0:3], v[170:173], v[212:215], v[0:3]
	s_setprio 0
	s_barrier

; #define PG8_STAGE(bufoff, gbase, voff) do { _Pragma("unroll") for (int _i = 0; _i < 2; ++_i) \
;         __builtin_amdgcn_global_load_lds((const unsigned*)((const char*)(gbase) + (voff)[_i]), (LAS unsigned*)(lds + (bufoff) + ldsw + _i * 8192), 16, 0, 0); } while (0)
; #define PG8_WAIT_V(n) asm volatile("s_waitcnt vmcnt(" #n ")" ::: "memory")
; #define PG8_BAR __builtin_amdgcn_s_barrier()
; template <class Epi, class Sched, bool ALIGN_EPI>
; __device__ __forceinline__ void gemm_phase(LAS unsigned char* lds, const Gemm g, const Sched& S, const Epi& E) {
;     ...
;     for (int i = 0; i < 2; ++i) { int R, C; stage_rc(tid * 16 + i * 8192, R, C); const int Rb = Epi::PERM ? ((R & ~31) + perm32(R & 31)) : R;
;         voffA[i] = (unsigned)(R * g.lda + C) * 2u; voffB[i] = (unsigned)(Rb * g.ldb + C) * 2u; }
;     const size_t kstep = (size_t)(BK * 2);
;     const size_t hstepA = (size_t)HALF * g.lda * 2, hstepB = (size_t)HALF * g.ldb * 2;
;     const size_t tstepA = 2 * hstepA, tstepB = 2 * hstepB;
;     const unsigned ldsw = (unsigned)wid * 1024u;
;     const int aoff = lds_byte(wr * 64 + fr, fq * 8), boff = lds_byte(wc * 32 + fr, fq * 8);
;     ...
;     Unit cur, nxt; int ui = 0;
;     if (!S.next(0, cur)) return;
;     f32x4 acc[2][2][4][2];
; #pragma unroll
;     for (int a = 0; a < 2; ++a)
; #pragma unroll
;         for (int b = 0; b < 2; ++b)
; #pragma unroll
;             for (int m = 0; m < 4; ++m)
; #pragma unroll
;                 for (int n = 0; n < 2; ++n) acc[a][b][m][n] = (f32x4){0.f, 0.f, 0.f, 0.f};
;     bf16x8 At[4][2], B0[2][2], B1[2][2];
;     const char* cA = (const char*)g.A + (size_t)cur.pm * tstepA; const char* cB = (const char*)g.Bt + (size_t)cur.pn * tstepB;
;     PG8_STAGE(PG8_SB(0, 0), cB, voffB); PG8_STAGE(PG8_SB(0, 1), cB + hstepB, voffB); PG8_STAGE(PG8_SA(0, 0), cA, voffA); PG8_STAGE(PG8_SA(0, 1), cA + hstepA, voffA);
;     if (wr == 1) PG8_BAR;
;     PG8_WAIT_V(2); PG8_BAR;
;     PG8_STAGE(PG8_SB(1, 0), cB + kstep, voffB); PG8_STAGE(PG8_SA(1, 0), cA + kstep, voffA); PG8_STAGE(PG8_SB(1, 1), cB + hstepB + kstep, voffB);
;     PG8_WAIT_V(6); PG8_BAR;
.LBB0_306:
	v_readlane_b32 s4, v255, 32
	v_readlane_b32 s5, v255, 33
	s_lshl_b64 s[4:5], s[4:5], 17
	s_add_u32 s8, s43, 0x2000
	v_writelane_b32 v255, s8, 56
	v_bfe_u32 v207, v13, 4, 2
	v_readlane_b32 s8, v255, 38
	s_addc_u32 s8, s8, 0
	s_add_u32 s4, s38, s4
	v_writelane_b32 v255, s8, 57
	v_writelane_b32 v255, s4, 60
	s_addc_u32 s4, s39, s5
	s_add_u32 s16, s16, 0x8100000
	s_addc_u32 s17, s17, 0
	s_add_u32 s20, s20, 0xe00000
	v_and_b32_e32 v211, 15, v13
	v_lshlrev_b32_e32 v15, 4, v207
	v_lshlrev_b32_e32 v13, 2, v13
	v_writelane_b32 v255, s4, 38
	s_addc_u32 s21, s21, 0
	s_and_b32 s91, s42, 3
	v_lshl_or_b32 v15, v211, 6, v15
	s_lshl_b32 s4, s41, 13
	v_and_b32_e32 v13, 32, v13
	s_add_i32 m0, s48, 0x18000
	v_lshl_add_u64 v[4:5], v[4:5], 0, s[12:13]
	s_lshl_b32 s8, s41, 6
	v_bitop3_b32 v16, v15, s4, v13 bitop3:0xde
	s_lshl_b32 s9, s91, 5
	s_lshl_b32 s4, s91, 12
	s_waitcnt vmcnt(2)
	s_barrier
	global_load_lds_dwordx4 v[4:5], off
	v_lshl_add_u64 v[2:3], v[2:3], 0, s[12:13]
	s_add_i32 m0, s48, 0x1a000
	s_add_i32 s66, s48, 0x8000
	s_add_i32 s86, s48, 0xa000
	v_bitop3_b32 v247, v15, s4, v13 bitop3:0xde
	global_load_lds_dwordx4 v[2:3], off
	v_lshl_add_u64 v[0:1], v[0:1], 0, s[12:13]
	s_mov_b32 m0, s66
	s_add_u32 s4, s46, 0x40080
	global_load_lds_dwordx4 v[0:1], off
	v_lshl_add_u64 v[0:1], v[6:7], 0, s[12:13]
	s_mov_b32 m0, s86
	s_addc_u32 s5, s47, 0
	global_load_lds_dwordx4 v[0:1], off
	s_add_i32 m0, s48, 0x1c000
	v_lshl_add_u64 v[0:1], s[4:5], 0, v[216:217]
	global_load_lds_dwordx4 v[0:1], off
	v_lshl_add_u64 v[0:1], s[4:5], 0, v[212:213]
	s_add_i32 m0, s48, 0x1e000
	s_cmpk_lt_u32 s40, 0x100
	global_load_lds_dwordx4 v[0:1], off
	v_lshlrev_b32_e32 v0, 14, v12
	s_cselect_b64 s[22:23], -1, 0
	s_and_b32 s4, s40, 0xffffff00
	s_lshl_b32 s5, s91, 6
	v_and_b32_e32 v0, 0xffff8000, v0
	s_or_b32 s40, s5, s4
	v_lshl_add_u32 v0, v11, 11, v0
	v_and_b32_e32 v1, 1, v12
	s_cmp_eq_u64 s[38:39], 0
	v_lshl_or_b32 v0, v1, 6, v0
	s_cselect_b64 s[42:43], -1, 0
	s_cmp_lg_u64 s[38:39], 0
	v_lshl_add_u32 v220, v14, 1, v0
	v_lshlrev_b32_e32 v0, 14, v8
	s_cselect_b64 s[38:39], -1, 0
	v_and_b32_e32 v0, 0xffff8000, v0
	s_xor_b64 s[42:43], s[42:43], -1
	s_waitcnt vmcnt(0)
	s_lshl_b32 s4, s91, 7
	v_lshl_add_u32 v0, v9, 11, v0
	v_and_b32_e32 v1, 1, v8
	v_writelane_b32 v255, s42, 58
	s_add_i32 s4, s4, 0
	v_lshl_or_b32 v0, v1, 6, v0
	v_writelane_b32 v255, s43, 59
	v_readlane_b32 s42, v254, 43
	s_add_i32 s41, s4, 0x20400
	s_add_i32 s4, s4, 0x20800
	v_mov_b32_e32 v221, v193
	v_lshl_add_u32 v222, v10, 1, v0
	v_mov_b32_e32 v223, v193
	s_mov_b32 s5, 0
	v_add_u32_e32 v248, 0, v16
	v_readlane_b32 s76, v254, 27
	s_mov_b32 s77, s42
	s_barrier
	v_readlane_b32 s43, v254, 44
	s_branch .LBB0_309

; #define PG8_STAGE(bufoff, gbase, voff) do { _Pragma("unroll") for (int _i = 0; _i < 2; ++_i) \
;         __builtin_amdgcn_global_load_lds((const unsigned*)((const char*)(gbase) + (voff)[_i]), (LAS unsigned*)(lds + (bufoff) + ldsw + _i * 8192), 16, 0, 0); } while (0)
; #define PG8_LDA(dst, b, h) do { _Pragma("unroll") for (int m = 0; m < 4; ++m) _Pragma("unroll") for (int k = 0; k < 2; ++k) dst[m][k] = *(const LAS bf16x8*)(lds + PG8_SA(b, h) + aoff + m * 2048 + k * 1024); } while (0)
; #define PG8_LDB(dst, b, h) do { _Pragma("unroll") for (int n = 0; n < 2; ++n) _Pragma("unroll") for (int k = 0; k < 2; ++k) dst[n][k] = *(const LAS bf16x8*)(lds + PG8_SB(b, h) + boff + n * 2048 + k * 1024); } while (0)
; #define PG8_MMA(ai, bj, At, Bt) do { __builtin_amdgcn_s_setprio(1); _Pragma("unroll") for (int m = 0; m < 4; ++m) _Pragma("unroll") for (int n = 0; n < 2; ++n) _Pragma("unroll") for (int k = 0; k < 2; ++k) \
;         acc[ai][bj][m][n] = __builtin_amdgcn_mfma_f32_16x16x32_bf16(Bt[n][k], At[m][k], acc[ai][bj][m][n], 0, 0, 0); __builtin_amdgcn_s_setprio(0); } while (0)
; #define PG8_BAR __builtin_amdgcn_s_barrier()
; template <class Epi, class Sched, bool ALIGN_EPI>
; __device__ __forceinline__ void gemm_phase(LAS unsigned char* lds, const Gemm g, const Sched& S, const Epi& E) {
;     ...
;         const bool has_next = S.next(ui + 1, nxt);
;         const char* nA = has_next ? (const char*)g.A + (size_t)nxt.pm * tstepA : cA; const char* nB = has_next ? (const char*)g.Bt + (size_t)nxt.pn * tstepB : cB;
;         for (int t = 0; t < nt; t += 2) {
;             const bool last = (t == nt - 2);
;             const char* a1 = cA + (size_t)(t + 1) * kstep;
;             const char* a2 = last ? nA : cA + (size_t)(t + 2) * kstep; const char* b2 = last ? nB : cB + (size_t)(t + 2) * kstep;
;             const char* a3 = a2 + kstep; const char* b3 = b2 + kstep;
;             PG8_LDB(B0, 0, 0); PG8_LDB(B1, 0, 1); PG8_SCHED; PG8_LDA(At, 0, 0); PG8_STAGE(PG8_SA(1, 1), a1 + hstepA, voffA);
;             PG8_WAIT_V(8); PG8_WAIT_L(0); PG8_BAR; PG8_MMA(0, 0, At, B0); PG8_MMA(0, 1, At, B1); PG8_BAR; PG8_SCHED;
;             PG8_LDA(At, 0, 1); PG8_STAGE(PG8_SB(0, 0), b2, voffB); PG8_STAGE(PG8_SB(0, 1), b2 + hstepB, voffB); PG8_STAGE(PG8_SA(0, 0), a2, voffA);
;             PG8_WAIT_V(8); PG8_WAIT_L(0); PG8_BAR; PG8_MMA(1, 0, At, B0); PG8_MMA(1, 1, At, B1); PG8_BAR; PG8_SCHED;
.LBB0_315:
	s_ashr_i32 s63, s62, 31
	s_lshl_b64 s[54:55], s[62:63], 19
	s_add_u32 s80, s33, s54
	s_addc_u32 s81, s51, s55
	s_and_b64 s[54:55], s[42:43], exec
	s_cselect_b32 s56, s81, s45
	s_cselect_b32 s57, s80, s44
	s_ashr_i32 s59, s58, 31
	s_lshl_b64 s[54:55], s[58:59], 19
	v_readlane_b32 s52, v255, 46
	s_add_u32 s84, s52, s54
	s_addc_u32 s85, s87, s55
	s_and_b64 s[54:55], s[42:43], exec
	s_cselect_b32 s59, s85, s47
	s_cselect_b32 s63, s84, s46
	s_add_u32 s44, s44, 0x40080
	s_addc_u32 s45, s45, 0
	s_add_u32 s64, s46, 0x100
	s_addc_u32 s65, s47, 0
	s_mov_b32 s92, -2
	s_add_u32 s46, s44, 0xfffc0080
	s_addc_u32 s47, s45, -1
	s_add_i32 s52, 0, 0x10000
	s_cmp_eq_u32 s92, 12
	s_cselect_b32 s55, s56, s47
	s_cselect_b32 s54, s57, s46
	s_cselect_b32 s47, s59, s65
	s_cselect_b32 s46, s63, s64
	s_add_i32 s53, 0, 0x14000
	v_add_u32_e32 v140, s52, v247
	v_add_u32_e32 v156, s53, v247
	ds_read_b128 v[104:107], v140
	ds_read_b128 v[112:115], v140 offset:1024
	ds_read_b128 v[136:139], v140 offset:2048
	ds_read_b128 v[140:143], v140 offset:3072
	ds_read_b128 v[144:147], v156
	ds_read_b128 v[148:151], v156 offset:1024
	ds_read_b128 v[152:155], v156 offset:2048
	ds_read_b128 v[156:159], v156 offset:3072
	v_lshl_add_u64 v[194:195], s[44:45], 0, v[220:221]
	s_add_i32 m0, s48, 0xc000
	ds_read_b128 v[160:163], v248
	ds_read_b128 v[164:167], v248 offset:1024
	ds_read_b128 v[168:171], v248 offset:2048
	ds_read_b128 v[172:175], v248 offset:3072
	ds_read_b128 v[176:179], v248 offset:4096
	ds_read_b128 v[180:183], v248 offset:5120
	ds_read_b128 v[184:187], v248 offset:6144
	ds_read_b128 v[188:191], v248 offset:7168
	global_load_lds_dwordx4 v[194:195], off
	v_lshl_add_u64 v[194:195], s[44:45], 0, v[222:223]
	s_add_i32 m0, s48, 0xe000
	s_nop 0
	global_load_lds_dwordx4 v[194:195], off
	s_waitcnt lgkmcnt(0)
	s_barrier
	s_setprio 1
	s_waitcnt lgkmcnt(0)
	v_mfma_f32_16x16x32_bf16 v[132:135], v[104:107], v[160:163], 0
	v_mfma_f32_16x16x32_bf16 v[128:131], v[136:139], v[160:163], 0
	v_mfma_f32_16x16x32_bf16 v[116:119], v[104:107], v[168:171], 0
	v_mfma_f32_16x16x32_bf16 v[108:111], v[136:139], v[168:171], 0
	v_mfma_f32_16x16x32_bf16 v[96:99], v[104:107], v[176:179], 0
	v_mfma_f32_16x16x32_bf16 v[88:91], v[136:139], v[176:179], 0
	v_mfma_f32_16x16x32_bf16 v[80:83], v[104:107], v[184:187], 0
	v_mfma_f32_16x16x32_bf16 v[72:75], v[136:139], v[184:187], 0
	v_mfma_f32_16x16x32_bf16 v[132:135], v[112:115], v[164:167], v[132:135]
	v_mfma_f32_16x16x32_bf16 v[128:131], v[140:143], v[164:167], v[128:131]
	v_mfma_f32_16x16x32_bf16 v[116:119], v[112:115], v[172:175], v[116:119]
	v_mfma_f32_16x16x32_bf16 v[108:111], v[140:143], v[172:175], v[108:111]
	v_mfma_f32_16x16x32_bf16 v[96:99], v[112:115], v[180:183], v[96:99]
	v_mfma_f32_16x16x32_bf16 v[88:91], v[140:143], v[180:183], v[88:91]
	v_mfma_f32_16x16x32_bf16 v[80:83], v[112:115], v[188:191], v[80:83]
	v_mfma_f32_16x16x32_bf16 v[72:75], v[140:143], v[188:191], v[72:75]
	s_setprio 0
	s_setprio 1
	v_mfma_f32_16x16x32_bf16 v[124:127], v[144:147], v[160:163], 0
	v_mfma_f32_16x16x32_bf16 v[120:123], v[152:155], v[160:163], 0
	v_mfma_f32_16x16x32_bf16 v[100:103], v[144:147], v[168:171], 0
	v_mfma_f32_16x16x32_bf16 v[92:95], v[152:155], v[168:171], 0
	v_mfma_f32_16x16x32_bf16 v[84:87], v[144:147], v[176:179], 0
	v_mfma_f32_16x16x32_bf16 v[76:79], v[152:155], v[176:179], 0
	v_mfma_f32_16x16x32_bf16 v[68:71], v[144:147], v[184:187], 0
	v_mfma_f32_16x16x32_bf16 v[64:67], v[152:155], v[184:187], 0
	v_mfma_f32_16x16x32_bf16 v[124:127], v[148:151], v[164:167], v[124:127]
	v_mfma_f32_16x16x32_bf16 v[120:123], v[156:159], v[164:167], v[120:123]
	v_mfma_f32_16x16x32_bf16 v[100:103], v[148:151], v[172:175], v[100:103]
	v_mfma_f32_16x16x32_bf16 v[92:95], v[156:159], v[172:175], v[92:95]
	v_mfma_f32_16x16x32_bf16 v[84:87], v[148:151], v[180:183], v[84:87]
	v_mfma_f32_16x16x32_bf16 v[76:79], v[156:159], v[180:183], v[76:79]
	v_mfma_f32_16x16x32_bf16 v[68:71], v[148:151], v[188:191], v[68:71]
	v_mfma_f32_16x16x32_bf16 v[64:67], v[156:159], v[188:191], v[64:67]
	s_setprio 0
	s_barrier
	s_add_i32 s52, s52, s50
	v_lshl_add_u64 v[194:195], s[46:47], 0, v[216:217]
	s_mov_b32 m0, s52
	ds_read_b128 v[160:163], v248 offset:16384
	ds_read_b128 v[164:167], v248 offset:17408
	ds_read_b128 v[168:171], v248 offset:18432
	ds_read_b128 v[172:175], v248 offset:19456
	ds_read_b128 v[176:179], v248 offset:20480
	ds_read_b128 v[180:183], v248 offset:21504
	ds_read_b128 v[184:187], v248 offset:22528
	ds_read_b128 v[188:191], v248 offset:23552
	global_load_lds_dwordx4 v[194:195], off
	s_add_i32 m0, s52, 0x2000
	s_add_u32 vcc_lo, s46, 0x40000
	v_lshl_add_u64 v[196:197], s[46:47], 0, v[212:213]
	s_addc_u32 vcc_hi, s47, 0
	s_add_i32 s52, s53, s50
	global_load_lds_dwordx4 v[196:197], off
	v_lshl_add_u64 v[198:199], vcc, 0, v[216:217]
	s_mov_b32 m0, s52
	v_lshl_add_u64 v[200:201], s[54:55], 0, v[214:215]
	global_load_lds_dwordx4 v[198:199], off
	v_lshl_add_u64 v[198:199], vcc, 0, v[212:213]
	s_add_i32 m0, s52, 0x2000
	s_nop 0
	global_load_lds_dwordx4 v[198:199], off
	v_lshl_add_u64 v[198:199], s[54:55], 0, v[218:219]
	s_mov_b32 m0, s48
	s_nop 0
	global_load_lds_dwordx4 v[198:199], off
	s_mov_b32 m0, s49
	s_nop 0
	global_load_lds_dwordx4 v[200:201], off
	s_waitcnt lgkmcnt(0)
	s_barrier
; #define PG8_STAGE(bufoff, gbase, voff) do { _Pragma("unroll") for (int _i = 0; _i < 2; ++_i) \
;         __builtin_amdgcn_global_load_lds((const unsigned*)((const char*)(gbase) + (voff)[_i]), (LAS unsigned*)(lds + (bufoff) + ldsw + _i * 8192), 16, 0, 0); } while (0)
; #define PG8_LDA(dst, b, h) do { _Pragma("unroll") for (int m = 0; m < 4; ++m) _Pragma("unroll") for (int k = 0; k < 2; ++k) dst[m][k] = *(const LAS bf16x8*)(lds + PG8_SA(b, h) + aoff + m * 2048 + k * 1024); } while (0)
; #define PG8_LDB(dst, b, h) do { _Pragma("unroll") for (int n = 0; n < 2; ++n) _Pragma("unroll") for (int k = 0; k < 2; ++k) dst[n][k] = *(const LAS bf16x8*)(lds + PG8_SB(b, h) + boff + n * 2048 + k * 1024); } while (0)
; #define PG8_MMA(ai, bj, At, Bt) do { __builtin_amdgcn_s_setprio(1); _Pragma("unroll") for (int m = 0; m < 4; ++m) _Pragma("unroll") for (int n = 0; n < 2; ++n) _Pragma("unroll") for (int k = 0; k < 2; ++k) \
;         acc[ai][bj][m][n] = __builtin_amdgcn_mfma_f32_16x16x32_bf16(Bt[n][k], At[m][k], acc[ai][bj][m][n], 0, 0, 0); __builtin_amdgcn_s_setprio(0); } while (0)
; #define PG8_WAIT_V(n) asm volatile("s_waitcnt vmcnt(" #n ")" ::: "memory")
; #define PG8_WAIT_L(n) asm volatile("s_waitcnt lgkmcnt(" #n ")" ::: "memory")
; #define PG8_BAR __builtin_amdgcn_s_barrier()
; #define PG8_SCHED __builtin_amdgcn_sched_barrier(0)
; template <class Epi, class Sched, bool ALIGN_EPI>
; __device__ __forceinline__ void gemm_phase(LAS unsigned char* lds, const Gemm g, const Sched& S, const Epi& E) {
;     ...
;             PG8_WAIT_V(8); PG8_WAIT_L(0); PG8_BAR; PG8_MMA(1, 0, At, B0); PG8_MMA(1, 1, At, B1); PG8_BAR; PG8_SCHED;
;             PG8_LDB(B0, 1, 0); PG8_LDB(B1, 1, 1); PG8_SCHED; PG8_LDA(At, 1, 0); PG8_STAGE(PG8_SA(0, 1), a2 + hstepA, voffA);
;             PG8_WAIT_V(8); PG8_WAIT_L(0); PG8_BAR; PG8_MMA(0, 0, At, B0); PG8_MMA(0, 1, At, B1); PG8_BAR; PG8_SCHED;
	s_setprio 1
	s_waitcnt lgkmcnt(0)
	v_mfma_f32_16x16x32_bf16 v[60:63], v[104:107], v[160:163], 0
	v_mfma_f32_16x16x32_bf16 v[56:59], v[136:139], v[160:163], 0
	v_mfma_f32_16x16x32_bf16 v[44:47], v[104:107], v[168:171], 0
	v_mfma_f32_16x16x32_bf16 v[40:43], v[136:139], v[168:171], 0
	v_mfma_f32_16x16x32_bf16 v[32:35], v[104:107], v[176:179], 0
	v_mfma_f32_16x16x32_bf16 v[24:27], v[136:139], v[176:179], 0
	v_mfma_f32_16x16x32_bf16 v[16:19], v[104:107], v[184:187], 0
	v_mfma_f32_16x16x32_bf16 v[8:11], v[136:139], v[184:187], 0
	v_mfma_f32_16x16x32_bf16 v[60:63], v[112:115], v[164:167], v[60:63]
	v_mfma_f32_16x16x32_bf16 v[56:59], v[140:143], v[164:167], v[56:59]
	v_mfma_f32_16x16x32_bf16 v[44:47], v[112:115], v[172:175], v[44:47]
	v_mfma_f32_16x16x32_bf16 v[40:43], v[140:143], v[172:175], v[40:43]
	v_mfma_f32_16x16x32_bf16 v[32:35], v[112:115], v[180:183], v[32:35]
	v_mfma_f32_16x16x32_bf16 v[24:27], v[140:143], v[180:183], v[24:27]
	v_mfma_f32_16x16x32_bf16 v[16:19], v[112:115], v[188:191], v[16:19]
	v_mfma_f32_16x16x32_bf16 v[8:11], v[140:143], v[188:191], v[8:11]
	s_setprio 0
	s_setprio 1
	v_mfma_f32_16x16x32_bf16 v[52:55], v[144:147], v[160:163], 0
	v_mfma_f32_16x16x32_bf16 v[48:51], v[152:155], v[160:163], 0
	v_mfma_f32_16x16x32_bf16 v[36:39], v[144:147], v[168:171], 0
	v_mfma_f32_16x16x32_bf16 v[28:31], v[152:155], v[168:171], 0
	v_mfma_f32_16x16x32_bf16 v[20:23], v[144:147], v[176:179], 0
	v_mfma_f32_16x16x32_bf16 v[12:15], v[152:155], v[176:179], 0
	v_mfma_f32_16x16x32_bf16 v[4:7], v[144:147], v[184:187], 0
	v_mfma_f32_16x16x32_bf16 v[0:3], v[152:155], v[184:187], 0
	v_mfma_f32_16x16x32_bf16 v[52:55], v[148:151], v[164:167], v[52:55]
	v_mfma_f32_16x16x32_bf16 v[48:51], v[156:159], v[164:167], v[48:51]
	v_mfma_f32_16x16x32_bf16 v[36:39], v[148:151], v[172:175], v[36:39]
	v_mfma_f32_16x16x32_bf16 v[28:31], v[156:159], v[172:175], v[28:31]
	v_mfma_f32_16x16x32_bf16 v[20:23], v[148:151], v[180:183], v[20:23]
	v_mfma_f32_16x16x32_bf16 v[12:15], v[156:159], v[180:183], v[12:15]
	v_mfma_f32_16x16x32_bf16 v[4:7], v[148:151], v[188:191], v[4:7]
	v_mfma_f32_16x16x32_bf16 v[0:3], v[156:159], v[188:191], v[0:3]
	s_setprio 0
	s_barrier
	s_add_i32 s52, 0, 0x18000
	s_add_i32 s53, 0, 0x1c000
	v_add_u32_e32 v140, s52, v247
	v_add_u32_e32 v156, s53, v247
	ds_read_b128 v[104:107], v140
	ds_read_b128 v[112:115], v140 offset:1024
	ds_read_b128 v[136:139], v140 offset:2048
	ds_read_b128 v[140:143], v140 offset:3072
	ds_read_b128 v[144:147], v156
	ds_read_b128 v[148:151], v156 offset:1024
	ds_read_b128 v[152:155], v156 offset:2048
	ds_read_b128 v[156:159], v156 offset:3072
	s_add_u32 s54, s54, 0x40000
	s_addc_u32 s55, s55, 0
	s_mov_b32 m0, s67
	v_lshl_add_u64 v[202:203], s[54:55], 0, v[218:219]
	ds_read_b128 v[160:163], v248 offset:32768
	ds_read_b128 v[164:167], v248 offset:33792
	ds_read_b128 v[168:171], v248 offset:34816
	ds_read_b128 v[172:175], v248 offset:35840
	ds_read_b128 v[176:179], v248 offset:36864
	ds_read_b128 v[180:183], v248 offset:37888
	ds_read_b128 v[184:187], v248 offset:38912
	ds_read_b128 v[188:191], v248 offset:39936
	global_load_lds_dwordx4 v[202:203], off
	v_lshl_add_u64 v[202:203], s[54:55], 0, v[214:215]
	s_mov_b32 m0, s90
	s_nop 0
	global_load_lds_dwordx4 v[202:203], off
	s_waitcnt vmcnt(8)
	s_waitcnt lgkmcnt(0)
	s_barrier
	s_setprio 1
	s_waitcnt lgkmcnt(0)
	v_mfma_f32_16x16x32_bf16 v[132:135], v[104:107], v[160:163], v[132:135]
	v_mfma_f32_16x16x32_bf16 v[128:131], v[136:139], v[160:163], v[128:131]
	v_mfma_f32_16x16x32_bf16 v[116:119], v[104:107], v[168:171], v[116:119]
	v_mfma_f32_16x16x32_bf16 v[108:111], v[136:139], v[168:171], v[108:111]
	v_mfma_f32_16x16x32_bf16 v[96:99], v[104:107], v[176:179], v[96:99]
	v_mfma_f32_16x16x32_bf16 v[88:91], v[136:139], v[176:179], v[88:91]
	v_mfma_f32_16x16x32_bf16 v[80:83], v[104:107], v[184:187], v[80:83]
	v_mfma_f32_16x16x32_bf16 v[72:75], v[136:139], v[184:187], v[72:75]
	v_mfma_f32_16x16x32_bf16 v[132:135], v[112:115], v[164:167], v[132:135]
	v_mfma_f32_16x16x32_bf16 v[128:131], v[140:143], v[164:167], v[128:131]
	v_mfma_f32_16x16x32_bf16 v[116:119], v[112:115], v[172:175], v[116:119]
	v_mfma_f32_16x16x32_bf16 v[108:111], v[140:143], v[172:175], v[108:111]
	v_mfma_f32_16x16x32_bf16 v[96:99], v[112:115], v[180:183], v[96:99]
	v_mfma_f32_16x16x32_bf16 v[88:91], v[140:143], v[180:183], v[88:91]
	v_mfma_f32_16x16x32_bf16 v[80:83], v[112:115], v[188:191], v[80:83]
	v_mfma_f32_16x16x32_bf16 v[72:75], v[140:143], v[188:191], v[72:75]
	s_setprio 0
	s_setprio 1
	v_mfma_f32_16x16x32_bf16 v[124:127], v[144:147], v[160:163], v[124:127]
	v_mfma_f32_16x16x32_bf16 v[120:123], v[152:155], v[160:163], v[120:123]
	v_mfma_f32_16x16x32_bf16 v[100:103], v[144:147], v[168:171], v[100:103]
	v_mfma_f32_16x16x32_bf16 v[92:95], v[152:155], v[168:171], v[92:95]
	v_mfma_f32_16x16x32_bf16 v[84:87], v[144:147], v[176:179], v[84:87]
	v_mfma_f32_16x16x32_bf16 v[76:79], v[152:155], v[176:179], v[76:79]
	v_mfma_f32_16x16x32_bf16 v[68:71], v[144:147], v[184:187], v[68:71]
	v_mfma_f32_16x16x32_bf16 v[64:67], v[152:155], v[184:187], v[64:67]
	v_mfma_f32_16x16x32_bf16 v[124:127], v[148:151], v[164:167], v[124:127]
	v_mfma_f32_16x16x32_bf16 v[120:123], v[156:159], v[164:167], v[120:123]
	v_mfma_f32_16x16x32_bf16 v[100:103], v[148:151], v[172:175], v[100:103]
	v_mfma_f32_16x16x32_bf16 v[92:95], v[156:159], v[172:175], v[92:95]
	v_mfma_f32_16x16x32_bf16 v[84:87], v[148:151], v[180:183], v[84:87]
	v_mfma_f32_16x16x32_bf16 v[76:79], v[156:159], v[180:183], v[76:79]
	v_mfma_f32_16x16x32_bf16 v[68:71], v[148:151], v[188:191], v[68:71]
	v_mfma_f32_16x16x32_bf16 v[64:67], v[156:159], v[188:191], v[64:67]
	s_setprio 0
	s_barrier
; #define PG8_STAGE(bufoff, gbase, voff) do { _Pragma("unroll") for (int _i = 0; _i < 2; ++_i) \
;         __builtin_amdgcn_global_load_lds((const unsigned*)((const char*)(gbase) + (voff)[_i]), (LAS unsigned*)(lds + (bufoff) + ldsw + _i * 8192), 16, 0, 0); } while (0)
; #define PG8_LDA(dst, b, h) do { _Pragma("unroll") for (int m = 0; m < 4; ++m) _Pragma("unroll") for (int k = 0; k < 2; ++k) dst[m][k] = *(const LAS bf16x8*)(lds + PG8_SA(b, h) + aoff + m * 2048 + k * 1024); } while (0)
; #define PG8_LDB(dst, b, h) do { _Pragma("unroll") for (int n = 0; n < 2; ++n) _Pragma("unroll") for (int k = 0; k < 2; ++k) dst[n][k] = *(const LAS bf16x8*)(lds + PG8_SB(b, h) + boff + n * 2048 + k * 1024); } while (0)
; #define PG8_WAIT_V(n) asm volatile("s_waitcnt vmcnt(" #n ")" ::: "memory")
; #define PG8_BAR __builtin_amdgcn_s_barrier()
; template <class Epi, class Sched, bool ALIGN_EPI>
; __device__ __forceinline__ void gemm_phase(LAS unsigned char* lds, const Gemm g, const Sched& S, const Epi& E) {
;     ...
;         for (int t = 0; t < nt; t += 2) {
;             const bool last = (t == nt - 2);
;             const char* a1 = cA + (size_t)(t + 1) * kstep;
;             const char* a2 = last ? nA : cA + (size_t)(t + 2) * kstep; const char* b2 = last ? nB : cB + (size_t)(t + 2) * kstep;
;             const char* a3 = a2 + kstep; const char* b3 = b2 + kstep;
;             PG8_LDB(B0, 0, 0); PG8_LDB(B1, 0, 1); PG8_SCHED; PG8_LDA(At, 0, 0); PG8_STAGE(PG8_SA(1, 1), a1 + hstepA, voffA);
;             PG8_WAIT_V(8); PG8_WAIT_L(0); PG8_BAR; PG8_MMA(0, 0, At, B0); PG8_MMA(0, 1, At, B1); PG8_BAR; PG8_SCHED;
;             PG8_LDA(At, 0, 1); PG8_STAGE(PG8_SB(0, 0), b2, voffB); PG8_STAGE(PG8_SB(0, 1), b2 + hstepB, voffB); PG8_STAGE(PG8_SA(0, 0), a2, voffA);
;             PG8_WAIT_V(8); PG8_WAIT_L(0); PG8_BAR; PG8_MMA(1, 0, At, B0); PG8_MMA(1, 1, At, B1); PG8_BAR; PG8_SCHED;
;             PG8_LDB(B0, 1, 0); PG8_LDB(B1, 1, 1); PG8_SCHED; PG8_LDA(At, 1, 0); PG8_STAGE(PG8_SA(0, 1), a2 + hstepA, voffA);
;             PG8_WAIT_V(8); PG8_WAIT_L(0); PG8_BAR; PG8_MMA(0, 0, At, B0); PG8_MMA(0, 1, At, B1); PG8_BAR; PG8_SCHED;
;             PG8_LDA(At, 1, 1); PG8_STAGE(PG8_SB(1, 0), b3, voffB); PG8_STAGE(PG8_SB(1, 1), b3 + hstepB, voffB); PG8_STAGE(PG8_SA(1, 0), a3, voffA);
;             PG8_WAIT_V(8); PG8_WAIT_L(0); PG8_BAR; PG8_MMA(1, 0, At, B0); PG8_MMA(1, 1, At, B1); PG8_BAR; PG8_SCHED;
	s_add_i32 s52, s52, s50
	v_lshl_add_u64 v[194:195], v[194:195], 0, s[12:13]
	s_mov_b32 m0, s52
	ds_read_b128 v[160:163], v248 offset:49152
	ds_read_b128 v[164:167], v248 offset:50176
	ds_read_b128 v[168:171], v248 offset:51200
	ds_read_b128 v[172:175], v248 offset:52224
	ds_read_b128 v[176:179], v248 offset:53248
	ds_read_b128 v[180:183], v248 offset:54272
	ds_read_b128 v[184:187], v248 offset:55296
	ds_read_b128 v[188:191], v248 offset:56320
	global_load_lds_dwordx4 v[194:195], off
	s_add_i32 m0, s52, 0x2000
	s_add_u32 s46, s46, 0x40080
	v_lshl_add_u64 v[194:195], v[196:197], 0, s[12:13]
	s_addc_u32 s47, s47, 0
	s_add_i32 s52, s53, s50
	global_load_lds_dwordx4 v[194:195], off
	v_lshl_add_u64 v[194:195], s[46:47], 0, v[216:217]
	s_mov_b32 m0, s52
	s_nop 0
	global_load_lds_dwordx4 v[194:195], off
	v_lshl_add_u64 v[194:195], s[46:47], 0, v[212:213]
	s_add_i32 m0, s52, 0x2000
	s_nop 0
	global_load_lds_dwordx4 v[194:195], off
	v_lshl_add_u64 v[194:195], v[198:199], 0, s[12:13]
	s_mov_b32 m0, s66
	s_nop 0
	global_load_lds_dwordx4 v[194:195], off
	v_lshl_add_u64 v[194:195], v[200:201], 0, s[12:13]
	s_mov_b32 m0, s86
	s_nop 0
	global_load_lds_dwordx4 v[194:195], off
	s_waitcnt vmcnt(8)
	s_waitcnt lgkmcnt(0)
	s_barrier
	s_setprio 1
	s_waitcnt lgkmcnt(0)
	v_mfma_f32_16x16x32_bf16 v[60:63], v[104:107], v[160:163], v[60:63]
	v_mfma_f32_16x16x32_bf16 v[56:59], v[136:139], v[160:163], v[56:59]
	v_mfma_f32_16x16x32_bf16 v[44:47], v[104:107], v[168:171], v[44:47]
	v_mfma_f32_16x16x32_bf16 v[40:43], v[136:139], v[168:171], v[40:43]
	v_mfma_f32_16x16x32_bf16 v[32:35], v[104:107], v[176:179], v[32:35]
	v_mfma_f32_16x16x32_bf16 v[24:27], v[136:139], v[176:179], v[24:27]
	v_mfma_f32_16x16x32_bf16 v[16:19], v[104:107], v[184:187], v[16:19]
	v_mfma_f32_16x16x32_bf16 v[8:11], v[136:139], v[184:187], v[8:11]
	v_mfma_f32_16x16x32_bf16 v[60:63], v[112:115], v[164:167], v[60:63]
	v_mfma_f32_16x16x32_bf16 v[56:59], v[140:143], v[164:167], v[56:59]
	v_mfma_f32_16x16x32_bf16 v[44:47], v[112:115], v[172:175], v[44:47]
	v_mfma_f32_16x16x32_bf16 v[40:43], v[140:143], v[172:175], v[40:43]
	v_mfma_f32_16x16x32_bf16 v[32:35], v[112:115], v[180:183], v[32:35]
	v_mfma_f32_16x16x32_bf16 v[24:27], v[140:143], v[180:183], v[24:27]
	v_mfma_f32_16x16x32_bf16 v[16:19], v[112:115], v[188:191], v[16:19]
	v_mfma_f32_16x16x32_bf16 v[8:11], v[140:143], v[188:191], v[8:11]
	s_setprio 0
	s_setprio 1
	v_mfma_f32_16x16x32_bf16 v[52:55], v[144:147], v[160:163], v[52:55]
	s_add_i32 s92, s92, 2
	v_mfma_f32_16x16x32_bf16 v[48:51], v[152:155], v[160:163], v[48:51]
	s_add_u32 s44, s44, 0x100
	v_mfma_f32_16x16x32_bf16 v[36:39], v[144:147], v[168:171], v[36:39]
	s_addc_u32 s45, s45, 0
	v_mfma_f32_16x16x32_bf16 v[28:31], v[152:155], v[168:171], v[28:31]
	s_add_u32 s64, s64, 0x100
	v_mfma_f32_16x16x32_bf16 v[20:23], v[144:147], v[176:179], v[20:23]
	s_addc_u32 s65, s65, 0
	v_mfma_f32_16x16x32_bf16 v[12:15], v[152:155], v[176:179], v[12:15]
	s_add_u32 s46, s44, 0xfffc0080
	v_mfma_f32_16x16x32_bf16 v[4:7], v[144:147], v[184:187], v[4:7]
	s_addc_u32 s47, s45, -1
	v_mfma_f32_16x16x32_bf16 v[0:3], v[152:155], v[184:187], v[0:3]
	s_add_i32 s52, 0, 0x10000
	v_mfma_f32_16x16x32_bf16 v[52:55], v[148:151], v[164:167], v[52:55]
	s_cmp_eq_u32 s92, 12
	v_mfma_f32_16x16x32_bf16 v[48:51], v[156:159], v[164:167], v[48:51]
	s_cselect_b32 s55, s56, s47
	v_mfma_f32_16x16x32_bf16 v[36:39], v[148:151], v[172:175], v[36:39]
	s_cselect_b32 s54, s57, s46
	v_mfma_f32_16x16x32_bf16 v[28:31], v[156:159], v[172:175], v[28:31]
	s_cselect_b32 s47, s59, s65
	v_mfma_f32_16x16x32_bf16 v[20:23], v[148:151], v[180:183], v[20:23]
	s_cselect_b32 s46, s63, s64
	v_mfma_f32_16x16x32_bf16 v[12:15], v[156:159], v[180:183], v[12:15]
	s_add_i32 s53, 0, 0x14000
	v_mfma_f32_16x16x32_bf16 v[4:7], v[148:151], v[188:191], v[4:7]
	s_cmp_gt_u32 s92, 13
	v_mfma_f32_16x16x32_bf16 v[0:3], v[156:159], v[188:191], v[0:3]
	s_setprio 0
	s_barrier

; #define PG8_STAGE(bufoff, gbase, voff) do { _Pragma("unroll") for (int _i = 0; _i < 2; ++_i) \
;         __builtin_amdgcn_global_load_lds((const unsigned*)((const char*)(gbase) + (voff)[_i]), (LAS unsigned*)(lds + (bufoff) + ldsw + _i * 8192), 16, 0, 0); } while (0)
; #define PG8_LDA(dst, b, h) do { _Pragma("unroll") for (int m = 0; m < 4; ++m) _Pragma("unroll") for (int k = 0; k < 2; ++k) dst[m][k] = *(const LAS bf16x8*)(lds + PG8_SA(b, h) + aoff + m * 2048 + k * 1024); } while (0)
; #define PG8_LDB(dst, b, h) do { _Pragma("unroll") for (int n = 0; n < 2; ++n) _Pragma("unroll") for (int k = 0; k < 2; ++k) dst[n][k] = *(const LAS bf16x8*)(lds + PG8_SB(b, h) + boff + n * 2048 + k * 1024); } while (0)
; #define PG8_MMA(ai, bj, At, Bt) do { __builtin_amdgcn_s_setprio(1); _Pragma("unroll") for (int m = 0; m < 4; ++m) _Pragma("unroll") for (int n = 0; n < 2; ++n) _Pragma("unroll") for (int k = 0; k < 2; ++k) \
;         acc[ai][bj][m][n] = __builtin_amdgcn_mfma_f32_16x16x32_bf16(Bt[n][k], At[m][k], acc[ai][bj][m][n], 0, 0, 0); __builtin_amdgcn_s_setprio(0); } while (0)
; #define PG8_WAIT_V(n) asm volatile("s_waitcnt vmcnt(" #n ")" ::: "memory")
; #define PG8_WAIT_L(n) asm volatile("s_waitcnt lgkmcnt(" #n ")" ::: "memory")
; #define PG8_BAR __builtin_amdgcn_s_barrier()
; #define PG8_SCHED __builtin_amdgcn_sched_barrier(0)
; template <class Epi, class Sched, bool ALIGN_EPI>
; __device__ __forceinline__ void gemm_phase(LAS unsigned char* lds, const Gemm g, const Sched& S, const Epi& E) {
;     ...
;         for (int t = 0; t < nt; t += 2) {
;             const bool last = (t == nt - 2);
;             const char* a1 = cA + (size_t)(t + 1) * kstep;
;             const char* a2 = last ? nA : cA + (size_t)(t + 2) * kstep; const char* b2 = last ? nB : cB + (size_t)(t + 2) * kstep;
;             const char* a3 = a2 + kstep; const char* b3 = b2 + kstep;
;             PG8_LDB(B0, 0, 0); PG8_LDB(B1, 0, 1); PG8_SCHED; PG8_LDA(At, 0, 0); PG8_STAGE(PG8_SA(1, 1), a1 + hstepA, voffA);
;             PG8_WAIT_V(8); PG8_WAIT_L(0); PG8_BAR; PG8_MMA(0, 0, At, B0); PG8_MMA(0, 1, At, B1); PG8_BAR; PG8_SCHED;
;             PG8_LDA(At, 0, 1); PG8_STAGE(PG8_SB(0, 0), b2, voffB); PG8_STAGE(PG8_SB(0, 1), b2 + hstepB, voffB); PG8_STAGE(PG8_SA(0, 0), a2, voffA);
;             PG8_WAIT_V(8); PG8_WAIT_L(0); PG8_BAR; PG8_MMA(1, 0, At, B0); PG8_MMA(1, 1, At, B1); PG8_BAR; PG8_SCHED;
.Lpf_noscale:
	v_add_u32_e32 v140, s52, v247
	v_add_u32_e32 v156, s53, v247
	ds_read_b128 v[104:107], v140
	ds_read_b128 v[112:115], v140 offset:1024
	ds_read_b128 v[136:139], v140 offset:2048
	ds_read_b128 v[140:143], v140 offset:3072
	ds_read_b128 v[144:147], v156
	ds_read_b128 v[148:151], v156 offset:1024
	ds_read_b128 v[152:155], v156 offset:2048
	ds_read_b128 v[156:159], v156 offset:3072
	v_lshl_add_u64 v[194:195], s[44:45], 0, v[220:221]
	s_add_i32 m0, s48, 0xc000
	ds_read_b128 v[160:163], v248
	ds_read_b128 v[164:167], v248 offset:1024
	ds_read_b128 v[168:171], v248 offset:2048
	ds_read_b128 v[172:175], v248 offset:3072
	ds_read_b128 v[176:179], v248 offset:4096
	ds_read_b128 v[180:183], v248 offset:5120
	ds_read_b128 v[184:187], v248 offset:6144
	ds_read_b128 v[188:191], v248 offset:7168
	global_load_lds_dwordx4 v[194:195], off
	v_lshl_add_u64 v[194:195], s[44:45], 0, v[222:223]
	s_add_i32 m0, s48, 0xe000
	s_nop 0
	global_load_lds_dwordx4 v[194:195], off
	s_waitcnt vmcnt(8)
	s_waitcnt lgkmcnt(0)
	s_barrier
	s_setprio 1
	s_waitcnt lgkmcnt(0)
	v_mfma_f32_16x16x32_bf16 v[132:135], v[104:107], v[160:163], v[132:135]
	v_mfma_f32_16x16x32_bf16 v[128:131], v[136:139], v[160:163], v[128:131]
	v_mfma_f32_16x16x32_bf16 v[116:119], v[104:107], v[168:171], v[116:119]
	v_mfma_f32_16x16x32_bf16 v[108:111], v[136:139], v[168:171], v[108:111]
	v_mfma_f32_16x16x32_bf16 v[96:99], v[104:107], v[176:179], v[96:99]
	v_mfma_f32_16x16x32_bf16 v[88:91], v[136:139], v[176:179], v[88:91]
	v_mfma_f32_16x16x32_bf16 v[80:83], v[104:107], v[184:187], v[80:83]
	v_mfma_f32_16x16x32_bf16 v[72:75], v[136:139], v[184:187], v[72:75]
	v_mfma_f32_16x16x32_bf16 v[132:135], v[112:115], v[164:167], v[132:135]
	v_mfma_f32_16x16x32_bf16 v[128:131], v[140:143], v[164:167], v[128:131]
	v_mfma_f32_16x16x32_bf16 v[116:119], v[112:115], v[172:175], v[116:119]
	v_mfma_f32_16x16x32_bf16 v[108:111], v[140:143], v[172:175], v[108:111]
	v_mfma_f32_16x16x32_bf16 v[96:99], v[112:115], v[180:183], v[96:99]
	v_mfma_f32_16x16x32_bf16 v[88:91], v[140:143], v[180:183], v[88:91]
	v_mfma_f32_16x16x32_bf16 v[80:83], v[112:115], v[188:191], v[80:83]
	v_mfma_f32_16x16x32_bf16 v[72:75], v[140:143], v[188:191], v[72:75]
	s_setprio 0
	s_setprio 1
	v_mfma_f32_16x16x32_bf16 v[124:127], v[144:147], v[160:163], v[124:127]
	v_mfma_f32_16x16x32_bf16 v[120:123], v[152:155], v[160:163], v[120:123]
	v_mfma_f32_16x16x32_bf16 v[100:103], v[144:147], v[168:171], v[100:103]
	v_mfma_f32_16x16x32_bf16 v[92:95], v[152:155], v[168:171], v[92:95]
	v_mfma_f32_16x16x32_bf16 v[84:87], v[144:147], v[176:179], v[84:87]
	v_mfma_f32_16x16x32_bf16 v[76:79], v[152:155], v[176:179], v[76:79]
	v_mfma_f32_16x16x32_bf16 v[68:71], v[144:147], v[184:187], v[68:71]
	v_mfma_f32_16x16x32_bf16 v[64:67], v[152:155], v[184:187], v[64:67]
	v_mfma_f32_16x16x32_bf16 v[124:127], v[148:151], v[164:167], v[124:127]
	v_mfma_f32_16x16x32_bf16 v[120:123], v[156:159], v[164:167], v[120:123]
	v_mfma_f32_16x16x32_bf16 v[100:103], v[148:151], v[172:175], v[100:103]
	v_mfma_f32_16x16x32_bf16 v[92:95], v[156:159], v[172:175], v[92:95]
	v_mfma_f32_16x16x32_bf16 v[84:87], v[148:151], v[180:183], v[84:87]
	v_mfma_f32_16x16x32_bf16 v[76:79], v[156:159], v[180:183], v[76:79]
	v_mfma_f32_16x16x32_bf16 v[68:71], v[148:151], v[188:191], v[68:71]
	v_mfma_f32_16x16x32_bf16 v[64:67], v[156:159], v[188:191], v[64:67]
	s_setprio 0
	s_barrier
	s_add_i32 s52, s52, s50
	v_lshl_add_u64 v[194:195], s[46:47], 0, v[216:217]
	s_mov_b32 m0, s52
	ds_read_b128 v[160:163], v248 offset:16384
	ds_read_b128 v[164:167], v248 offset:17408
	ds_read_b128 v[168:171], v248 offset:18432
	ds_read_b128 v[172:175], v248 offset:19456
	ds_read_b128 v[176:179], v248 offset:20480
	ds_read_b128 v[180:183], v248 offset:21504
	ds_read_b128 v[184:187], v248 offset:22528
	ds_read_b128 v[188:191], v248 offset:23552
	global_load_lds_dwordx4 v[194:195], off
	s_add_i32 m0, s52, 0x2000
	s_add_u32 vcc_lo, s46, 0x40000
	v_lshl_add_u64 v[196:197], s[46:47], 0, v[212:213]
	s_addc_u32 vcc_hi, s47, 0
	s_add_i32 s52, s53, s50
	global_load_lds_dwordx4 v[196:197], off
	v_lshl_add_u64 v[198:199], vcc, 0, v[216:217]
	s_mov_b32 m0, s52
	v_lshl_add_u64 v[200:201], s[54:55], 0, v[214:215]
	global_load_lds_dwordx4 v[198:199], off
	v_lshl_add_u64 v[198:199], vcc, 0, v[212:213]
	s_add_i32 m0, s52, 0x2000
	s_nop 0
	global_load_lds_dwordx4 v[198:199], off
	v_lshl_add_u64 v[198:199], s[54:55], 0, v[218:219]
	s_mov_b32 m0, s48
	s_nop 0
	global_load_lds_dwordx4 v[198:199], off
	s_mov_b32 m0, s49
	s_nop 0
	global_load_lds_dwordx4 v[200:201], off
	s_waitcnt vmcnt(8)
	s_waitcnt lgkmcnt(0)
	s_barrier
; #define PG8_STAGE(bufoff, gbase, voff) do { _Pragma("unroll") for (int _i = 0; _i < 2; ++_i) \
;         __builtin_amdgcn_global_load_lds((const unsigned*)((const char*)(gbase) + (voff)[_i]), (LAS unsigned*)(lds + (bufoff) + ldsw + _i * 8192), 16, 0, 0); } while (0)
; #define PG8_LDA(dst, b, h) do { _Pragma("unroll") for (int m = 0; m < 4; ++m) _Pragma("unroll") for (int k = 0; k < 2; ++k) dst[m][k] = *(const LAS bf16x8*)(lds + PG8_SA(b, h) + aoff + m * 2048 + k * 1024); } while (0)
; #define PG8_LDB(dst, b, h) do { _Pragma("unroll") for (int n = 0; n < 2; ++n) _Pragma("unroll") for (int k = 0; k < 2; ++k) dst[n][k] = *(const LAS bf16x8*)(lds + PG8_SB(b, h) + boff + n * 2048 + k * 1024); } while (0)
; #define PG8_MMA(ai, bj, At, Bt) do { __builtin_amdgcn_s_setprio(1); _Pragma("unroll") for (int m = 0; m < 4; ++m) _Pragma("unroll") for (int n = 0; n < 2; ++n) _Pragma("unroll") for (int k = 0; k < 2; ++k) \
;         acc[ai][bj][m][n] = __builtin_amdgcn_mfma_f32_16x16x32_bf16(Bt[n][k], At[m][k], acc[ai][bj][m][n], 0, 0, 0); __builtin_amdgcn_s_setprio(0); } while (0)
; #define PG8_WAIT_V(n) asm volatile("s_waitcnt vmcnt(" #n ")" ::: "memory")
; #define PG8_WAIT_L(n) asm volatile("s_waitcnt lgkmcnt(" #n ")" ::: "memory")
; #define PG8_BAR __builtin_amdgcn_s_barrier()
; #define PG8_SCHED __builtin_amdgcn_sched_barrier(0)
; template <class Epi, class Sched, bool ALIGN_EPI>
; __device__ __forceinline__ void gemm_phase(LAS unsigned char* lds, const Gemm g, const Sched& S, const Epi& E) {
;     ...
;             PG8_WAIT_V(8); PG8_WAIT_L(0); PG8_BAR; PG8_MMA(1, 0, At, B0); PG8_MMA(1, 1, At, B1); PG8_BAR; PG8_SCHED;
;             PG8_LDB(B0, 1, 0); PG8_LDB(B1, 1, 1); PG8_SCHED; PG8_LDA(At, 1, 0); PG8_STAGE(PG8_SA(0, 1), a2 + hstepA, voffA);
;             PG8_WAIT_V(8); PG8_WAIT_L(0); PG8_BAR; PG8_MMA(0, 0, At, B0); PG8_MMA(0, 1, At, B1); PG8_BAR; PG8_SCHED;
	s_setprio 1
	s_waitcnt lgkmcnt(0)
	v_mfma_f32_16x16x32_bf16 v[60:63], v[104:107], v[160:163], v[60:63]
	v_mfma_f32_16x16x32_bf16 v[56:59], v[136:139], v[160:163], v[56:59]
	v_mfma_f32_16x16x32_bf16 v[44:47], v[104:107], v[168:171], v[44:47]
	v_mfma_f32_16x16x32_bf16 v[40:43], v[136:139], v[168:171], v[40:43]
	v_mfma_f32_16x16x32_bf16 v[32:35], v[104:107], v[176:179], v[32:35]
	v_mfma_f32_16x16x32_bf16 v[24:27], v[136:139], v[176:179], v[24:27]
	v_mfma_f32_16x16x32_bf16 v[16:19], v[104:107], v[184:187], v[16:19]
	v_mfma_f32_16x16x32_bf16 v[8:11], v[136:139], v[184:187], v[8:11]
	v_mfma_f32_16x16x32_bf16 v[60:63], v[112:115], v[164:167], v[60:63]
	v_mfma_f32_16x16x32_bf16 v[56:59], v[140:143], v[164:167], v[56:59]
	v_mfma_f32_16x16x32_bf16 v[44:47], v[112:115], v[172:175], v[44:47]
	v_mfma_f32_16x16x32_bf16 v[40:43], v[140:143], v[172:175], v[40:43]
	v_mfma_f32_16x16x32_bf16 v[32:35], v[112:115], v[180:183], v[32:35]
	v_mfma_f32_16x16x32_bf16 v[24:27], v[140:143], v[180:183], v[24:27]
	v_mfma_f32_16x16x32_bf16 v[16:19], v[112:115], v[188:191], v[16:19]
	v_mfma_f32_16x16x32_bf16 v[8:11], v[140:143], v[188:191], v[8:11]
	s_setprio 0
	s_setprio 1
	v_mfma_f32_16x16x32_bf16 v[52:55], v[144:147], v[160:163], v[52:55]
	v_mfma_f32_16x16x32_bf16 v[48:51], v[152:155], v[160:163], v[48:51]
	v_mfma_f32_16x16x32_bf16 v[36:39], v[144:147], v[168:171], v[36:39]
	v_mfma_f32_16x16x32_bf16 v[28:31], v[152:155], v[168:171], v[28:31]
	v_mfma_f32_16x16x32_bf16 v[20:23], v[144:147], v[176:179], v[20:23]
	v_mfma_f32_16x16x32_bf16 v[12:15], v[152:155], v[176:179], v[12:15]
	v_mfma_f32_16x16x32_bf16 v[4:7], v[144:147], v[184:187], v[4:7]
	v_mfma_f32_16x16x32_bf16 v[0:3], v[152:155], v[184:187], v[0:3]
	v_mfma_f32_16x16x32_bf16 v[52:55], v[148:151], v[164:167], v[52:55]
	v_mfma_f32_16x16x32_bf16 v[48:51], v[156:159], v[164:167], v[48:51]
	v_mfma_f32_16x16x32_bf16 v[36:39], v[148:151], v[172:175], v[36:39]
	v_mfma_f32_16x16x32_bf16 v[28:31], v[156:159], v[172:175], v[28:31]
	v_mfma_f32_16x16x32_bf16 v[20:23], v[148:151], v[180:183], v[20:23]
	v_mfma_f32_16x16x32_bf16 v[12:15], v[156:159], v[180:183], v[12:15]
	v_mfma_f32_16x16x32_bf16 v[4:7], v[148:151], v[188:191], v[4:7]
	v_mfma_f32_16x16x32_bf16 v[0:3], v[156:159], v[188:191], v[0:3]
	s_setprio 0
	s_barrier
	s_add_i32 s52, 0, 0x18000
	s_add_i32 s53, 0, 0x1c000
	v_add_u32_e32 v140, s52, v247
	v_add_u32_e32 v156, s53, v247
	ds_read_b128 v[104:107], v140
	ds_read_b128 v[112:115], v140 offset:1024
	ds_read_b128 v[136:139], v140 offset:2048
	ds_read_b128 v[140:143], v140 offset:3072
	ds_read_b128 v[144:147], v156
	ds_read_b128 v[148:151], v156 offset:1024
	ds_read_b128 v[152:155], v156 offset:2048
	ds_read_b128 v[156:159], v156 offset:3072
	s_add_u32 s54, s54, 0x40000
	s_addc_u32 s55, s55, 0
	s_mov_b32 m0, s67
	v_lshl_add_u64 v[202:203], s[54:55], 0, v[218:219]
	ds_read_b128 v[160:163], v248 offset:32768
	ds_read_b128 v[164:167], v248 offset:33792
	ds_read_b128 v[168:171], v248 offset:34816
	ds_read_b128 v[172:175], v248 offset:35840
	ds_read_b128 v[176:179], v248 offset:36864
	ds_read_b128 v[180:183], v248 offset:37888
	ds_read_b128 v[184:187], v248 offset:38912
	ds_read_b128 v[188:191], v248 offset:39936
	global_load_lds_dwordx4 v[202:203], off
	v_lshl_add_u64 v[202:203], s[54:55], 0, v[214:215]
	s_mov_b32 m0, s90
	s_nop 0
	global_load_lds_dwordx4 v[202:203], off
	s_waitcnt vmcnt(8)
	s_waitcnt lgkmcnt(0)
	s_barrier
	s_setprio 1
	s_waitcnt lgkmcnt(0)
	v_mfma_f32_16x16x32_bf16 v[132:135], v[104:107], v[160:163], v[132:135]
	v_mfma_f32_16x16x32_bf16 v[128:131], v[136:139], v[160:163], v[128:131]
	v_mfma_f32_16x16x32_bf16 v[116:119], v[104:107], v[168:171], v[116:119]
	v_mfma_f32_16x16x32_bf16 v[108:111], v[136:139], v[168:171], v[108:111]
	v_mfma_f32_16x16x32_bf16 v[96:99], v[104:107], v[176:179], v[96:99]
	v_mfma_f32_16x16x32_bf16 v[88:91], v[136:139], v[176:179], v[88:91]
	v_mfma_f32_16x16x32_bf16 v[80:83], v[104:107], v[184:187], v[80:83]
	v_mfma_f32_16x16x32_bf16 v[72:75], v[136:139], v[184:187], v[72:75]
	v_mfma_f32_16x16x32_bf16 v[132:135], v[112:115], v[164:167], v[132:135]
	v_mfma_f32_16x16x32_bf16 v[128:131], v[140:143], v[164:167], v[128:131]
	v_mfma_f32_16x16x32_bf16 v[116:119], v[112:115], v[172:175], v[116:119]
	v_mfma_f32_16x16x32_bf16 v[108:111], v[140:143], v[172:175], v[108:111]
	v_mfma_f32_16x16x32_bf16 v[96:99], v[112:115], v[180:183], v[96:99]
	v_mfma_f32_16x16x32_bf16 v[88:91], v[140:143], v[180:183], v[88:91]
	v_mfma_f32_16x16x32_bf16 v[80:83], v[112:115], v[188:191], v[80:83]
	v_mfma_f32_16x16x32_bf16 v[72:75], v[140:143], v[188:191], v[72:75]
	s_setprio 0
	s_setprio 1
	v_mfma_f32_16x16x32_bf16 v[124:127], v[144:147], v[160:163], v[124:127]
	v_mfma_f32_16x16x32_bf16 v[120:123], v[152:155], v[160:163], v[120:123]
	v_mfma_f32_16x16x32_bf16 v[100:103], v[144:147], v[168:171], v[100:103]
	v_mfma_f32_16x16x32_bf16 v[92:95], v[152:155], v[168:171], v[92:95]
	v_mfma_f32_16x16x32_bf16 v[84:87], v[144:147], v[176:179], v[84:87]
	v_mfma_f32_16x16x32_bf16 v[76:79], v[152:155], v[176:179], v[76:79]
	v_mfma_f32_16x16x32_bf16 v[68:71], v[144:147], v[184:187], v[68:71]
	v_mfma_f32_16x16x32_bf16 v[64:67], v[152:155], v[184:187], v[64:67]
	v_mfma_f32_16x16x32_bf16 v[124:127], v[148:151], v[164:167], v[124:127]
	v_mfma_f32_16x16x32_bf16 v[120:123], v[156:159], v[164:167], v[120:123]
	v_mfma_f32_16x16x32_bf16 v[100:103], v[148:151], v[172:175], v[100:103]
	v_mfma_f32_16x16x32_bf16 v[92:95], v[156:159], v[172:175], v[92:95]
	v_mfma_f32_16x16x32_bf16 v[84:87], v[148:151], v[180:183], v[84:87]
	v_mfma_f32_16x16x32_bf16 v[76:79], v[156:159], v[180:183], v[76:79]
	v_mfma_f32_16x16x32_bf16 v[68:71], v[148:151], v[188:191], v[68:71]
	v_mfma_f32_16x16x32_bf16 v[64:67], v[156:159], v[188:191], v[64:67]
	s_setprio 0
	s_barrier
; #define PG8_STAGE(bufoff, gbase, voff) do { _Pragma("unroll") for (int _i = 0; _i < 2; ++_i) \
;         __builtin_amdgcn_global_load_lds((const unsigned*)((const char*)(gbase) + (voff)[_i]), (LAS unsigned*)(lds + (bufoff) + ldsw + _i * 8192), 16, 0, 0); } while (0)
; #define PG8_LDA(dst, b, h) do { _Pragma("unroll") for (int m = 0; m < 4; ++m) _Pragma("unroll") for (int k = 0; k < 2; ++k) dst[m][k] = *(const LAS bf16x8*)(lds + PG8_SA(b, h) + aoff + m * 2048 + k * 1024); } while (0)
; #define PG8_LDB(dst, b, h) do { _Pragma("unroll") for (int n = 0; n < 2; ++n) _Pragma("unroll") for (int k = 0; k < 2; ++k) dst[n][k] = *(const LAS bf16x8*)(lds + PG8_SB(b, h) + boff + n * 2048 + k * 1024); } while (0)
; #define PG8_MMA(ai, bj, At, Bt) do { __builtin_amdgcn_s_setprio(1); _Pragma("unroll") for (int m = 0; m < 4; ++m) _Pragma("unroll") for (int n = 0; n < 2; ++n) _Pragma("unroll") for (int k = 0; k < 2; ++k) \
;         acc[ai][bj][m][n] = __builtin_amdgcn_mfma_f32_16x16x32_bf16(Bt[n][k], At[m][k], acc[ai][bj][m][n], 0, 0, 0); __builtin_amdgcn_s_setprio(0); } while (0)
; #define PG8_WAIT_V(n) asm volatile("s_waitcnt vmcnt(" #n ")" ::: "memory")
; #define PG8_WAIT_L(n) asm volatile("s_waitcnt lgkmcnt(" #n ")" ::: "memory")
; #define PG8_BAR __builtin_amdgcn_s_barrier()
; #define PG8_SCHED __builtin_amdgcn_sched_barrier(0)
; template <class Epi, class Sched, bool ALIGN_EPI>
; __device__ __forceinline__ void gemm_phase(LAS unsigned char* lds, const Gemm g, const Sched& S, const Epi& E) {
;     ...
;         for (int t = 0; t < nt; t += 2) {
;             const bool last = (t == nt - 2);
;             const char* a1 = cA + (size_t)(t + 1) * kstep;
;             const char* a2 = last ? nA : cA + (size_t)(t + 2) * kstep; const char* b2 = last ? nB : cB + (size_t)(t + 2) * kstep;
;             const char* a3 = a2 + kstep; const char* b3 = b2 + kstep;
;     ...
;             PG8_LDB(B0, 1, 0); PG8_LDB(B1, 1, 1); PG8_SCHED; PG8_LDA(At, 1, 0); PG8_STAGE(PG8_SA(0, 1), a2 + hstepA, voffA);
;             PG8_WAIT_V(8); PG8_WAIT_L(0); PG8_BAR; PG8_MMA(0, 0, At, B0); PG8_MMA(0, 1, At, B1); PG8_BAR; PG8_SCHED;
;             PG8_LDA(At, 1, 1); PG8_STAGE(PG8_SB(1, 0), b3, voffB); PG8_STAGE(PG8_SB(1, 1), b3 + hstepB, voffB); PG8_STAGE(PG8_SA(1, 0), a3, voffA);
;             PG8_WAIT_V(8); PG8_WAIT_L(0); PG8_BAR; PG8_MMA(1, 0, At, B0); PG8_MMA(1, 1, At, B1); PG8_BAR; PG8_SCHED;
	s_add_i32 s52, s52, s50
	v_lshl_add_u64 v[194:195], v[194:195], 0, s[12:13]
	s_mov_b32 m0, s52
	ds_read_b128 v[160:163], v248 offset:49152
	ds_read_b128 v[164:167], v248 offset:50176
	ds_read_b128 v[168:171], v248 offset:51200
	ds_read_b128 v[172:175], v248 offset:52224
	ds_read_b128 v[176:179], v248 offset:53248
	ds_read_b128 v[180:183], v248 offset:54272
	ds_read_b128 v[184:187], v248 offset:55296
	ds_read_b128 v[188:191], v248 offset:56320
	global_load_lds_dwordx4 v[194:195], off
	s_add_i32 m0, s52, 0x2000
	s_add_u32 s46, s46, 0x40080
	v_lshl_add_u64 v[194:195], v[196:197], 0, s[12:13]
	s_addc_u32 s47, s47, 0
	s_add_i32 s52, s53, s50
	global_load_lds_dwordx4 v[194:195], off
	v_lshl_add_u64 v[194:195], s[46:47], 0, v[216:217]
	s_mov_b32 m0, s52
	s_nop 0
	global_load_lds_dwordx4 v[194:195], off
	v_lshl_add_u64 v[194:195], s[46:47], 0, v[212:213]
	s_add_i32 m0, s52, 0x2000
	s_nop 0
	global_load_lds_dwordx4 v[194:195], off
	v_lshl_add_u64 v[194:195], v[198:199], 0, s[12:13]
	s_mov_b32 m0, s66
	s_nop 0
	global_load_lds_dwordx4 v[194:195], off
	v_lshl_add_u64 v[194:195], v[200:201], 0, s[12:13]
	s_mov_b32 m0, s86
	s_nop 0
	global_load_lds_dwordx4 v[194:195], off
	s_waitcnt vmcnt(8)
	s_waitcnt lgkmcnt(0)
	s_barrier
	s_setprio 1
	s_waitcnt lgkmcnt(0)
	v_mfma_f32_16x16x32_bf16 v[60:63], v[104:107], v[160:163], v[60:63]
	v_mfma_f32_16x16x32_bf16 v[56:59], v[136:139], v[160:163], v[56:59]
	v_mfma_f32_16x16x32_bf16 v[44:47], v[104:107], v[168:171], v[44:47]
	v_mfma_f32_16x16x32_bf16 v[40:43], v[136:139], v[168:171], v[40:43]
	v_mfma_f32_16x16x32_bf16 v[32:35], v[104:107], v[176:179], v[32:35]
	v_mfma_f32_16x16x32_bf16 v[24:27], v[136:139], v[176:179], v[24:27]
	v_mfma_f32_16x16x32_bf16 v[16:19], v[104:107], v[184:187], v[16:19]
	v_mfma_f32_16x16x32_bf16 v[8:11], v[136:139], v[184:187], v[8:11]
	v_mfma_f32_16x16x32_bf16 v[60:63], v[112:115], v[164:167], v[60:63]
	v_mfma_f32_16x16x32_bf16 v[56:59], v[140:143], v[164:167], v[56:59]
	v_mfma_f32_16x16x32_bf16 v[44:47], v[112:115], v[172:175], v[44:47]
	v_mfma_f32_16x16x32_bf16 v[40:43], v[140:143], v[172:175], v[40:43]
	v_mfma_f32_16x16x32_bf16 v[32:35], v[112:115], v[180:183], v[32:35]
	v_mfma_f32_16x16x32_bf16 v[24:27], v[140:143], v[180:183], v[24:27]
	v_mfma_f32_16x16x32_bf16 v[16:19], v[112:115], v[188:191], v[16:19]
	v_mfma_f32_16x16x32_bf16 v[8:11], v[140:143], v[188:191], v[8:11]
	s_setprio 0
	s_setprio 1
	v_mfma_f32_16x16x32_bf16 v[52:55], v[144:147], v[160:163], v[52:55]
	s_add_i32 s92, s92, 2
	v_mfma_f32_16x16x32_bf16 v[48:51], v[152:155], v[160:163], v[48:51]
	s_add_u32 s44, s44, 0x100
	v_mfma_f32_16x16x32_bf16 v[36:39], v[144:147], v[168:171], v[36:39]
	s_addc_u32 s45, s45, 0
	v_mfma_f32_16x16x32_bf16 v[28:31], v[152:155], v[168:171], v[28:31]
	s_add_u32 s64, s64, 0x100
	v_mfma_f32_16x16x32_bf16 v[20:23], v[144:147], v[176:179], v[20:23]
	s_addc_u32 s65, s65, 0
	v_mfma_f32_16x16x32_bf16 v[12:15], v[152:155], v[176:179], v[12:15]
	s_add_u32 s46, s44, 0xfffc0080
	v_mfma_f32_16x16x32_bf16 v[4:7], v[144:147], v[184:187], v[4:7]
	s_addc_u32 s47, s45, -1
	v_mfma_f32_16x16x32_bf16 v[0:3], v[152:155], v[184:187], v[0:3]
	s_add_i32 s52, 0, 0x10000
	v_mfma_f32_16x16x32_bf16 v[52:55], v[148:151], v[164:167], v[52:55]
	s_cmp_eq_u32 s92, 12
	v_mfma_f32_16x16x32_bf16 v[48:51], v[156:159], v[164:167], v[48:51]
	s_cselect_b32 s55, s56, s47
	v_mfma_f32_16x16x32_bf16 v[36:39], v[148:151], v[172:175], v[36:39]
	s_cselect_b32 s54, s57, s46
	v_mfma_f32_16x16x32_bf16 v[28:31], v[156:159], v[172:175], v[28:31]
	s_cselect_b32 s47, s59, s65
	v_mfma_f32_16x16x32_bf16 v[20:23], v[148:151], v[180:183], v[20:23]
	s_cselect_b32 s46, s63, s64
	v_mfma_f32_16x16x32_bf16 v[12:15], v[156:159], v[180:183], v[12:15]
	s_add_i32 s53, 0, 0x14000
	v_mfma_f32_16x16x32_bf16 v[4:7], v[148:151], v[188:191], v[4:7]
	s_cmp_gt_u32 s92, 13
	v_mfma_f32_16x16x32_bf16 v[0:3], v[156:159], v[188:191], v[0:3]
	s_setprio 0
	s_barrier
	s_cbranch_scc0 .LBB0_316
; __device__ __forceinline__ float sq4(f32x4 v) { return (v[0] * v[0] + v[1] * v[1]) + (v[2] * v[2] + v[3] * v[3]); }
;     __device__ __forceinline__ void operator()(const f32x4 (&acc)[2][2][4][2], const Unit& u, int wr, int wc, int fr, int fq) const {
;     ...
;                 const int row = u.pm * 256 + ai * 128 + wr * 64 + m * 16 + fr;
;                 const float rs = rsl[ai * 128 + wr * 64 + m * 16 + fr];
;                 f32x4 v[2][2]; float ss = 0.f;
; #pragma unroll
;                 for (int bj = 0; bj < 2; ++bj)
; #pragma unroll
;                     for (int n = 0; n < 2; ++n) { v[bj][n] = acc[ai][bj][m][n] * rs + sw[bj][n]; ss += sq4(v[bj][n]); }
	s_and_b32 vcc_lo, s5, 1
	s_mul_i32 vcc_lo, vcc_lo, 0x3800
	s_and_b32 vcc_hi, s40, 0x100
	s_add_i32 vcc_lo, vcc_lo, 0x20000
	s_add_i32 vcc_lo, vcc_lo, vcc_hi
	v_lshl_add_u32 v176, v211, 2, vcc_lo
	ds_read_b32 v160, v176
	ds_read_b32 v162, v176 offset:64
	ds_read_b32 v164, v176 offset:128
	ds_read_b32 v166, v176 offset:192
	ds_read_b32 v168, v176 offset:512
	ds_read_b32 v170, v176 offset:576
	ds_read_b32 v172, v176 offset:640
	ds_read_b32 v174, v176 offset:704
	s_waitcnt lgkmcnt(0)
	v_pk_mul_f32 v[120:121], v[160:161], v[120:121] op_sel_hi:[0,1]
	v_pk_mul_f32 v[122:123], v[160:161], v[122:123] op_sel_hi:[0,1]
	v_pk_mul_f32 v[124:125], v[160:161], v[124:125] op_sel_hi:[0,1]
	v_pk_mul_f32 v[126:127], v[160:161], v[126:127] op_sel_hi:[0,1]
	v_pk_mul_f32 v[128:129], v[160:161], v[128:129] op_sel_hi:[0,1]
	v_pk_mul_f32 v[130:131], v[160:161], v[130:131] op_sel_hi:[0,1]
	v_pk_mul_f32 v[132:133], v[160:161], v[132:133] op_sel_hi:[0,1]
	v_pk_mul_f32 v[134:135], v[160:161], v[134:135] op_sel_hi:[0,1]
	v_pk_mul_f32 v[92:93], v[162:163], v[92:93] op_sel_hi:[0,1]
	v_pk_mul_f32 v[94:95], v[162:163], v[94:95] op_sel_hi:[0,1]
	v_pk_mul_f32 v[100:101], v[162:163], v[100:101] op_sel_hi:[0,1]
	v_pk_mul_f32 v[102:103], v[162:163], v[102:103] op_sel_hi:[0,1]
	v_pk_mul_f32 v[108:109], v[162:163], v[108:109] op_sel_hi:[0,1]
	v_pk_mul_f32 v[110:111], v[162:163], v[110:111] op_sel_hi:[0,1]
	v_pk_mul_f32 v[116:117], v[162:163], v[116:117] op_sel_hi:[0,1]
	v_pk_mul_f32 v[118:119], v[162:163], v[118:119] op_sel_hi:[0,1]
	v_pk_mul_f32 v[76:77], v[164:165], v[76:77] op_sel_hi:[0,1]
	v_pk_mul_f32 v[78:79], v[164:165], v[78:79] op_sel_hi:[0,1]
	v_pk_mul_f32 v[84:85], v[164:165], v[84:85] op_sel_hi:[0,1]
	v_pk_mul_f32 v[86:87], v[164:165], v[86:87] op_sel_hi:[0,1]
	v_pk_mul_f32 v[88:89], v[164:165], v[88:89] op_sel_hi:[0,1]
	v_pk_mul_f32 v[90:91], v[164:165], v[90:91] op_sel_hi:[0,1]
	v_pk_mul_f32 v[96:97], v[164:165], v[96:97] op_sel_hi:[0,1]
	v_pk_mul_f32 v[98:99], v[164:165], v[98:99] op_sel_hi:[0,1]
	v_pk_mul_f32 v[64:65], v[166:167], v[64:65] op_sel_hi:[0,1]
	v_pk_mul_f32 v[66:67], v[166:167], v[66:67] op_sel_hi:[0,1]
	v_pk_mul_f32 v[68:69], v[166:167], v[68:69] op_sel_hi:[0,1]
	v_pk_mul_f32 v[70:71], v[166:167], v[70:71] op_sel_hi:[0,1]
	v_pk_mul_f32 v[72:73], v[166:167], v[72:73] op_sel_hi:[0,1]
	v_pk_mul_f32 v[74:75], v[166:167], v[74:75] op_sel_hi:[0,1]
	v_pk_mul_f32 v[80:81], v[166:167], v[80:81] op_sel_hi:[0,1]
	v_pk_mul_f32 v[82:83], v[166:167], v[82:83] op_sel_hi:[0,1]
	v_pk_mul_f32 v[48:49], v[168:169], v[48:49] op_sel_hi:[0,1]
	v_pk_mul_f32 v[50:51], v[168:169], v[50:51] op_sel_hi:[0,1]
	v_pk_mul_f32 v[52:53], v[168:169], v[52:53] op_sel_hi:[0,1]
	v_pk_mul_f32 v[54:55], v[168:169], v[54:55] op_sel_hi:[0,1]
	v_pk_mul_f32 v[56:57], v[168:169], v[56:57] op_sel_hi:[0,1]
	v_pk_mul_f32 v[58:59], v[168:169], v[58:59] op_sel_hi:[0,1]
	v_pk_mul_f32 v[60:61], v[168:169], v[60:61] op_sel_hi:[0,1]
	v_pk_mul_f32 v[62:63], v[168:169], v[62:63] op_sel_hi:[0,1]
	v_pk_mul_f32 v[28:29], v[170:171], v[28:29] op_sel_hi:[0,1]
	v_pk_mul_f32 v[30:31], v[170:171], v[30:31] op_sel_hi:[0,1]
	v_pk_mul_f32 v[36:37], v[170:171], v[36:37] op_sel_hi:[0,1]
	v_pk_mul_f32 v[38:39], v[170:171], v[38:39] op_sel_hi:[0,1]
	v_pk_mul_f32 v[40:41], v[170:171], v[40:41] op_sel_hi:[0,1]
	v_pk_mul_f32 v[42:43], v[170:171], v[42:43] op_sel_hi:[0,1]
	v_pk_mul_f32 v[44:45], v[170:171], v[44:45] op_sel_hi:[0,1]
	v_pk_mul_f32 v[46:47], v[170:171], v[46:47] op_sel_hi:[0,1]
	v_pk_mul_f32 v[12:13], v[172:173], v[12:13] op_sel_hi:[0,1]
	v_pk_mul_f32 v[14:15], v[172:173], v[14:15] op_sel_hi:[0,1]
	v_pk_mul_f32 v[20:21], v[172:173], v[20:21] op_sel_hi:[0,1]
	v_pk_mul_f32 v[22:23], v[172:173], v[22:23] op_sel_hi:[0,1]
	v_pk_mul_f32 v[24:25], v[172:173], v[24:25] op_sel_hi:[0,1]
	v_pk_mul_f32 v[26:27], v[172:173], v[26:27] op_sel_hi:[0,1]
	v_pk_mul_f32 v[32:33], v[172:173], v[32:33] op_sel_hi:[0,1]
	v_pk_mul_f32 v[34:35], v[172:173], v[34:35] op_sel_hi:[0,1]
	v_pk_mul_f32 v[0:1], v[174:175], v[0:1] op_sel_hi:[0,1]
	v_pk_mul_f32 v[2:3], v[174:175], v[2:3] op_sel_hi:[0,1]
	v_pk_mul_f32 v[4:5], v[174:175], v[4:5] op_sel_hi:[0,1]
	v_pk_mul_f32 v[6:7], v[174:175], v[6:7] op_sel_hi:[0,1]
	v_pk_mul_f32 v[8:9], v[174:175], v[8:9] op_sel_hi:[0,1]
	v_pk_mul_f32 v[10:11], v[174:175], v[10:11] op_sel_hi:[0,1]
	v_pk_mul_f32 v[16:17], v[174:175], v[16:17] op_sel_hi:[0,1]
	v_pk_mul_f32 v[18:19], v[174:175], v[18:19] op_sel_hi:[0,1]
	s_and_b64 vcc, exec, s[22:23]
	s_cbranch_vccz .LBB0_319
	s_barrier
